# counted waits: the vmcnt wait and the lgkmcnt(0) wait in front of every load-segment barrier merged into one s_waitcnt (36 sites), on top of the in-place P5 statistics version
# speedup vs baseline: 1.0051x; 1.0021x over previous
.Lnb_p1:
	s_add_i32 s7, s4, 0xfff84000
	s_cmp_eq_u32 s6, 28
	s_cselect_b32 s17, s0, s7
	s_cselect_b32 s16, s1, s5
	s_or_b32 s7, s17, 0x4000
	s_mov_b32 m0, s79
	s_nop 0
	buffer_load_dwordx4 v242, s[24:27], s4 offen lds
	s_nop 0
	s_mov_b32 m0, s83
	s_nop 0
	buffer_load_dwordx4 v243, s[24:27], s4 offen lds
	s_waitcnt vmcnt(24) lgkmcnt(0)
	s_barrier
	s_waitcnt lgkmcnt(7)
	v_mfma_f32_16x16x32_bf16 v[180:183], v[16:19], v[192:195], 0
	v_mfma_f32_16x16x32_bf16 v[164:167], v[24:27], v[192:195], 0
	s_waitcnt lgkmcnt(5)
	v_mfma_f32_16x16x32_bf16 v[148:151], v[16:19], v[200:203], 0
	v_mfma_f32_16x16x32_bf16 v[140:143], v[24:27], v[200:203], 0
	s_waitcnt lgkmcnt(3)
	v_mfma_f32_16x16x32_bf16 v[132:135], v[16:19], v[220:223], 0
	v_mfma_f32_16x16x32_bf16 v[124:127], v[24:27], v[220:223], 0
	s_waitcnt lgkmcnt(1)
	v_mfma_f32_16x16x32_bf16 v[116:119], v[16:19], v[228:231], 0
	v_mfma_f32_16x16x32_bf16 v[108:111], v[24:27], v[228:231], 0
	v_mfma_f32_16x16x32_bf16 v[180:183], v[20:23], v[196:199], v[180:183]
	v_mfma_f32_16x16x32_bf16 v[164:167], v[28:31], v[196:199], v[164:167]
	v_mfma_f32_16x16x32_bf16 v[148:151], v[20:23], v[204:207], v[148:151]
	v_mfma_f32_16x16x32_bf16 v[140:143], v[28:31], v[204:207], v[140:143]
	v_mfma_f32_16x16x32_bf16 v[132:135], v[20:23], v[224:227], v[132:135]
	v_mfma_f32_16x16x32_bf16 v[124:127], v[28:31], v[224:227], v[124:127]
	s_waitcnt lgkmcnt(0)
	v_mfma_f32_16x16x32_bf16 v[116:119], v[20:23], v[246:249], v[116:119]
	v_mfma_f32_16x16x32_bf16 v[108:111], v[28:31], v[246:249], v[108:111]
	v_mfma_f32_16x16x32_bf16 v[172:175], v[152:155], v[192:195], 0
	v_mfma_f32_16x16x32_bf16 v[156:159], v[168:171], v[192:195], 0
	v_mfma_f32_16x16x32_bf16 v[144:147], v[152:155], v[200:203], 0
	v_mfma_f32_16x16x32_bf16 v[136:139], v[168:171], v[200:203], 0
	v_mfma_f32_16x16x32_bf16 v[128:131], v[152:155], v[220:223], 0
	v_mfma_f32_16x16x32_bf16 v[120:123], v[168:171], v[220:223], 0
	v_mfma_f32_16x16x32_bf16 v[112:115], v[152:155], v[228:231], 0
	v_mfma_f32_16x16x32_bf16 v[104:107], v[168:171], v[228:231], 0
	v_mfma_f32_16x16x32_bf16 v[172:175], v[160:163], v[196:199], v[172:175]
	v_mfma_f32_16x16x32_bf16 v[156:159], v[176:179], v[196:199], v[156:159]
	v_mfma_f32_16x16x32_bf16 v[144:147], v[160:163], v[204:207], v[144:147]
	v_mfma_f32_16x16x32_bf16 v[136:139], v[176:179], v[204:207], v[136:139]
	v_mfma_f32_16x16x32_bf16 v[128:131], v[160:163], v[224:227], v[128:131]
	v_mfma_f32_16x16x32_bf16 v[120:123], v[176:179], v[224:227], v[120:123]
	v_mfma_f32_16x16x32_bf16 v[112:115], v[160:163], v[246:249], v[112:115]
	v_mfma_f32_16x16x32_bf16 v[104:107], v[176:179], v[246:249], v[104:107]
	s_barrier
	ds_read_b128 v[192:195], v245 offset:16384
	ds_read_b128 v[196:199], v245 offset:17408
	ds_read_b128 v[200:203], v245 offset:18432
	ds_read_b128 v[204:207], v245 offset:19456
	ds_read_b128 v[220:223], v245 offset:20480
	ds_read_b128 v[224:227], v245 offset:21504
	ds_read_b128 v[228:231], v245 offset:22528
	ds_read_b128 v[246:249], v245 offset:23552
	s_mov_b32 m0, s51
	s_nop 0
	buffer_load_dwordx4 v242, s[56:59], s16 offen lds
	s_add_i32 s18, s16, 0x80000
	s_mov_b32 m0, s52
	s_nop 0
	buffer_load_dwordx4 v243, s[56:59], s16 offen lds
	s_nop 0
	s_mov_b32 m0, s53
	s_nop 0
	buffer_load_dwordx4 v242, s[56:59], s18 offen lds
	s_nop 0
	s_mov_b32 m0, s55
	s_nop 0
	buffer_load_dwordx4 v243, s[56:59], s18 offen lds
	s_nop 0
	s_mov_b32 m0, s31
	s_nop 0
	buffer_load_dwordx4 v242, s[24:27], s17 offen lds
	s_nop 0
	s_mov_b32 m0, s68
	s_nop 0
	buffer_load_dwordx4 v243, s[24:27], s17 offen lds
	s_waitcnt vmcnt(24) lgkmcnt(0)
	s_barrier
	s_waitcnt lgkmcnt(7)
	v_mfma_f32_16x16x32_bf16 v[76:79], v[16:19], v[192:195], 0
	v_mfma_f32_16x16x32_bf16 v[68:71], v[24:27], v[192:195], 0
	s_waitcnt lgkmcnt(5)
	v_mfma_f32_16x16x32_bf16 v[60:63], v[16:19], v[200:203], 0
	v_mfma_f32_16x16x32_bf16 v[52:55], v[24:27], v[200:203], 0
	s_waitcnt lgkmcnt(3)
	v_mfma_f32_16x16x32_bf16 v[44:47], v[16:19], v[220:223], 0
	v_mfma_f32_16x16x32_bf16 v[36:39], v[24:27], v[220:223], 0
	s_waitcnt lgkmcnt(1)
	v_mfma_f32_16x16x32_bf16 v[12:15], v[16:19], v[228:231], 0
	v_mfma_f32_16x16x32_bf16 v[4:7], v[24:27], v[228:231], 0
	v_mfma_f32_16x16x32_bf16 v[76:79], v[20:23], v[196:199], v[76:79]
	v_mfma_f32_16x16x32_bf16 v[68:71], v[28:31], v[196:199], v[68:71]
	v_mfma_f32_16x16x32_bf16 v[60:63], v[20:23], v[204:207], v[60:63]
	v_mfma_f32_16x16x32_bf16 v[52:55], v[28:31], v[204:207], v[52:55]
	v_mfma_f32_16x16x32_bf16 v[44:47], v[20:23], v[224:227], v[44:47]
	v_mfma_f32_16x16x32_bf16 v[36:39], v[28:31], v[224:227], v[36:39]
	s_waitcnt lgkmcnt(0)
	v_mfma_f32_16x16x32_bf16 v[12:15], v[20:23], v[246:249], v[12:15]
	v_mfma_f32_16x16x32_bf16 v[4:7], v[28:31], v[246:249], v[4:7]
	v_mfma_f32_16x16x32_bf16 v[40:43], v[152:155], v[220:223], 0
	v_mfma_f32_16x16x32_bf16 v[32:35], v[168:171], v[220:223], 0
	v_mfma_f32_16x16x32_bf16 v[8:11], v[152:155], v[228:231], 0
	v_mfma_f32_16x16x32_bf16 v[0:3], v[168:171], v[228:231], 0
	v_mfma_f32_16x16x32_bf16 v[16:19], v[152:155], v[192:195], 0
	v_mfma_f32_16x16x32_bf16 v[20:23], v[168:171], v[192:195], 0
	v_mfma_f32_16x16x32_bf16 v[24:27], v[152:155], v[200:203], 0
	v_mfma_f32_16x16x32_bf16 v[28:31], v[168:171], v[200:203], 0
	v_mfma_f32_16x16x32_bf16 v[40:43], v[160:163], v[224:227], v[40:43]
	v_mfma_f32_16x16x32_bf16 v[32:35], v[176:179], v[224:227], v[32:35]
	v_mfma_f32_16x16x32_bf16 v[8:11], v[160:163], v[246:249], v[8:11]
	v_mfma_f32_16x16x32_bf16 v[0:3], v[176:179], v[246:249], v[0:3]
	v_mfma_f32_16x16x32_bf16 v[16:19], v[160:163], v[196:199], v[16:19]
	v_mfma_f32_16x16x32_bf16 v[20:23], v[176:179], v[196:199], v[20:23]
	v_mfma_f32_16x16x32_bf16 v[24:27], v[160:163], v[204:207], v[24:27]
	v_mfma_f32_16x16x32_bf16 v[28:31], v[176:179], v[204:207], v[28:31]
	s_barrier
	v_add_u32_e32 v72, 0x18000, v83
	v_add_u32_e32 v80, 0x1c000, v83
	ds_read_b128 v[48:51], v72
	ds_read_b128 v[56:59], v72 offset:1024
	ds_read_b128 v[64:67], v72 offset:2048
	ds_read_b128 v[72:75], v72 offset:3072
	ds_read_b128 v[152:155], v80
	ds_read_b128 v[160:163], v80 offset:1024
	ds_read_b128 v[168:171], v80 offset:2048
	ds_read_b128 v[176:179], v80 offset:3072
	ds_read_b128 v[192:195], v245 offset:32768
	ds_read_b128 v[196:199], v245 offset:33792
	ds_read_b128 v[200:203], v245 offset:34816
	ds_read_b128 v[204:207], v245 offset:35840
	ds_read_b128 v[220:223], v245 offset:36864
	ds_read_b128 v[224:227], v245 offset:37888
	ds_read_b128 v[228:231], v245 offset:38912
	ds_read_b128 v[246:249], v245 offset:39936
	s_add_i32 s17, s17, 0x80000
	s_mov_b32 m0, s69
	s_nop 0
	buffer_load_dwordx4 v242, s[24:27], s17 offen lds
	s_nop 0
	s_mov_b32 m0, s70
	s_nop 0
	buffer_load_dwordx4 v243, s[24:27], s17 offen lds
	s_waitcnt vmcnt(8) lgkmcnt(0)
	s_barrier
	s_waitcnt lgkmcnt(7)
	v_mfma_f32_16x16x32_bf16 v[180:183], v[48:51], v[192:195], v[180:183]
	v_mfma_f32_16x16x32_bf16 v[164:167], v[64:67], v[192:195], v[164:167]
	s_waitcnt lgkmcnt(5)
	v_mfma_f32_16x16x32_bf16 v[148:151], v[48:51], v[200:203], v[148:151]
	v_mfma_f32_16x16x32_bf16 v[140:143], v[64:67], v[200:203], v[140:143]
	s_waitcnt lgkmcnt(3)
	v_mfma_f32_16x16x32_bf16 v[132:135], v[48:51], v[220:223], v[132:135]
	v_mfma_f32_16x16x32_bf16 v[124:127], v[64:67], v[220:223], v[124:127]
	s_waitcnt lgkmcnt(1)
	v_mfma_f32_16x16x32_bf16 v[116:119], v[48:51], v[228:231], v[116:119]
	v_mfma_f32_16x16x32_bf16 v[108:111], v[64:67], v[228:231], v[108:111]
	v_mfma_f32_16x16x32_bf16 v[180:183], v[56:59], v[196:199], v[180:183]
	v_mfma_f32_16x16x32_bf16 v[164:167], v[72:75], v[196:199], v[164:167]
	v_mfma_f32_16x16x32_bf16 v[148:151], v[56:59], v[204:207], v[148:151]
	v_mfma_f32_16x16x32_bf16 v[140:143], v[72:75], v[204:207], v[140:143]
	v_mfma_f32_16x16x32_bf16 v[132:135], v[56:59], v[224:227], v[132:135]
	v_mfma_f32_16x16x32_bf16 v[124:127], v[72:75], v[224:227], v[124:127]
	s_waitcnt lgkmcnt(0)
	v_mfma_f32_16x16x32_bf16 v[116:119], v[56:59], v[246:249], v[116:119]
	v_mfma_f32_16x16x32_bf16 v[108:111], v[72:75], v[246:249], v[108:111]
	v_mfma_f32_16x16x32_bf16 v[172:175], v[152:155], v[192:195], v[172:175]
	v_mfma_f32_16x16x32_bf16 v[156:159], v[168:171], v[192:195], v[156:159]
	v_mfma_f32_16x16x32_bf16 v[144:147], v[152:155], v[200:203], v[144:147]
	v_mfma_f32_16x16x32_bf16 v[136:139], v[168:171], v[200:203], v[136:139]
	v_mfma_f32_16x16x32_bf16 v[128:131], v[152:155], v[220:223], v[128:131]
	v_mfma_f32_16x16x32_bf16 v[120:123], v[168:171], v[220:223], v[120:123]
	v_mfma_f32_16x16x32_bf16 v[112:115], v[152:155], v[228:231], v[112:115]
	v_mfma_f32_16x16x32_bf16 v[104:107], v[168:171], v[228:231], v[104:107]
	v_mfma_f32_16x16x32_bf16 v[172:175], v[160:163], v[196:199], v[172:175]
	v_mfma_f32_16x16x32_bf16 v[156:159], v[176:179], v[196:199], v[156:159]
	v_mfma_f32_16x16x32_bf16 v[144:147], v[160:163], v[204:207], v[144:147]
	v_mfma_f32_16x16x32_bf16 v[136:139], v[176:179], v[204:207], v[136:139]
	v_mfma_f32_16x16x32_bf16 v[128:131], v[160:163], v[224:227], v[128:131]
	v_mfma_f32_16x16x32_bf16 v[120:123], v[176:179], v[224:227], v[120:123]
	v_mfma_f32_16x16x32_bf16 v[112:115], v[160:163], v[246:249], v[112:115]
	v_mfma_f32_16x16x32_bf16 v[104:107], v[176:179], v[246:249], v[104:107]
	s_barrier
	ds_read_b128 v[192:195], v245 offset:49152
	ds_read_b128 v[196:199], v245 offset:50176
	ds_read_b128 v[200:203], v245 offset:51200
	ds_read_b128 v[204:207], v245 offset:52224
	ds_read_b128 v[220:223], v245 offset:53248
	ds_read_b128 v[224:227], v245 offset:54272
	ds_read_b128 v[228:231], v245 offset:55296
	ds_read_b128 v[246:249], v245 offset:56320
	s_or_b32 s17, s16, 0x4000
	s_mov_b32 m0, s73
	s_nop 0
	buffer_load_dwordx4 v242, s[56:59], s17 offen lds
	s_add_i32 s16, s16, 0x84000
	s_mov_b32 m0, s74
	s_nop 0
	buffer_load_dwordx4 v243, s[56:59], s17 offen lds
	s_nop 0
	s_mov_b32 m0, s77
	s_nop 0
	buffer_load_dwordx4 v242, s[56:59], s16 offen lds
	s_nop 0
	s_mov_b32 m0, s78
	s_nop 0
	buffer_load_dwordx4 v243, s[56:59], s16 offen lds
	s_nop 0
	s_mov_b32 m0, s75
	s_nop 0
	buffer_load_dwordx4 v242, s[24:27], s7 offen lds
	s_nop 0
	s_mov_b32 m0, s76
	s_nop 0
	buffer_load_dwordx4 v243, s[24:27], s7 offen lds
	s_waitcnt vmcnt(8) lgkmcnt(0)
	s_barrier
	s_waitcnt lgkmcnt(7)
	v_mfma_f32_16x16x32_bf16 v[76:79], v[48:51], v[192:195], v[76:79]
	v_mfma_f32_16x16x32_bf16 v[68:71], v[64:67], v[192:195], v[68:71]
	s_waitcnt lgkmcnt(5)
	v_mfma_f32_16x16x32_bf16 v[60:63], v[48:51], v[200:203], v[60:63]
	v_mfma_f32_16x16x32_bf16 v[52:55], v[64:67], v[200:203], v[52:55]
	s_waitcnt lgkmcnt(3)
	v_mfma_f32_16x16x32_bf16 v[44:47], v[48:51], v[220:223], v[44:47]
	v_mfma_f32_16x16x32_bf16 v[36:39], v[64:67], v[220:223], v[36:39]
	s_waitcnt lgkmcnt(1)
	v_mfma_f32_16x16x32_bf16 v[12:15], v[48:51], v[228:231], v[12:15]
	v_mfma_f32_16x16x32_bf16 v[4:7], v[64:67], v[228:231], v[4:7]
	v_mfma_f32_16x16x32_bf16 v[76:79], v[56:59], v[196:199], v[76:79]
	v_mfma_f32_16x16x32_bf16 v[68:71], v[72:75], v[196:199], v[68:71]
	v_mfma_f32_16x16x32_bf16 v[60:63], v[56:59], v[204:207], v[60:63]
	v_mfma_f32_16x16x32_bf16 v[52:55], v[72:75], v[204:207], v[52:55]
	v_mfma_f32_16x16x32_bf16 v[44:47], v[56:59], v[224:227], v[44:47]
	v_mfma_f32_16x16x32_bf16 v[36:39], v[72:75], v[224:227], v[36:39]
	s_waitcnt lgkmcnt(0)
	v_mfma_f32_16x16x32_bf16 v[12:15], v[56:59], v[246:249], v[12:15]
	v_mfma_f32_16x16x32_bf16 v[4:7], v[72:75], v[246:249], v[4:7]
	v_mfma_f32_16x16x32_bf16 v[16:19], v[152:155], v[192:195], v[16:19]
	v_mfma_f32_16x16x32_bf16 v[72:75], v[160:163], v[196:199], v[16:19]
	v_mfma_f32_16x16x32_bf16 v[16:19], v[168:171], v[192:195], v[20:23]
	v_mfma_f32_16x16x32_bf16 v[64:67], v[176:179], v[196:199], v[16:19]
	v_mfma_f32_16x16x32_bf16 v[16:19], v[152:155], v[200:203], v[24:27]
	v_mfma_f32_16x16x32_bf16 v[56:59], v[160:163], v[204:207], v[16:19]
	v_mfma_f32_16x16x32_bf16 v[16:19], v[168:171], v[200:203], v[28:31]
	v_mfma_f32_16x16x32_bf16 v[48:51], v[176:179], v[204:207], v[16:19]
	v_mfma_f32_16x16x32_bf16 v[16:19], v[152:155], v[220:223], v[40:43]
	v_mfma_f32_16x16x32_bf16 v[40:43], v[160:163], v[224:227], v[16:19]
	v_mfma_f32_16x16x32_bf16 v[16:19], v[168:171], v[220:223], v[32:35]
	v_mfma_f32_16x16x32_bf16 v[8:11], v[152:155], v[228:231], v[8:11]
	v_mfma_f32_16x16x32_bf16 v[0:3], v[168:171], v[228:231], v[0:3]
	v_mfma_f32_16x16x32_bf16 v[32:35], v[176:179], v[224:227], v[16:19]
	v_mfma_f32_16x16x32_bf16 v[8:11], v[160:163], v[246:249], v[8:11]
	v_mfma_f32_16x16x32_bf16 v[0:3], v[176:179], v[246:249], v[0:3]
	s_barrier
	s_add_i32 s6, s6, 2
	s_add_i32 s4, s4, 0x8000
	s_add_i32 s5, s5, 0x8000
.LBB0_143:
	v_add_u32_e32 v28, 0x10000, v83
	v_add_u32_e32 v80, 0x14000, v83
	ds_read_b128 v[16:19], v28
	ds_read_b128 v[20:23], v28 offset:1024
	ds_read_b128 v[24:27], v28 offset:2048
	ds_read_b128 v[28:31], v28 offset:3072
	ds_read_b128 v[152:155], v80
	ds_read_b128 v[160:163], v80 offset:1024
	ds_read_b128 v[168:171], v80 offset:2048
	ds_read_b128 v[176:179], v80 offset:3072
	s_add_i32 s7, s4, 0xfff84000
	s_cmp_eq_u32 s6, 28
	s_cselect_b32 s17, s0, s7
	s_cselect_b32 s16, s1, s5
	s_or_b32 s7, s17, 0x4000
	ds_read_b128 v[192:195], v245
	ds_read_b128 v[196:199], v245 offset:1024
	ds_read_b128 v[200:203], v245 offset:2048
	ds_read_b128 v[204:207], v245 offset:3072
	ds_read_b128 v[220:223], v245 offset:4096
	ds_read_b128 v[224:227], v245 offset:5120
	ds_read_b128 v[228:231], v245 offset:6144
	ds_read_b128 v[246:249], v245 offset:7168
	s_mov_b32 m0, s79
	s_nop 0
	buffer_load_dwordx4 v242, s[24:27], s4 offen lds
	s_nop 0
	s_mov_b32 m0, s83
	s_nop 0
	buffer_load_dwordx4 v243, s[24:27], s4 offen lds
	s_waitcnt vmcnt(8) lgkmcnt(0)
	s_barrier
	s_waitcnt lgkmcnt(7)
	v_mfma_f32_16x16x32_bf16 v[180:183], v[16:19], v[192:195], v[180:183]
	v_mfma_f32_16x16x32_bf16 v[164:167], v[24:27], v[192:195], v[164:167]
	s_waitcnt lgkmcnt(5)
	v_mfma_f32_16x16x32_bf16 v[148:151], v[16:19], v[200:203], v[148:151]
	v_mfma_f32_16x16x32_bf16 v[140:143], v[24:27], v[200:203], v[140:143]
	s_waitcnt lgkmcnt(3)
	v_mfma_f32_16x16x32_bf16 v[132:135], v[16:19], v[220:223], v[132:135]
	v_mfma_f32_16x16x32_bf16 v[124:127], v[24:27], v[220:223], v[124:127]
	s_waitcnt lgkmcnt(1)
	v_mfma_f32_16x16x32_bf16 v[116:119], v[16:19], v[228:231], v[116:119]
	v_mfma_f32_16x16x32_bf16 v[108:111], v[24:27], v[228:231], v[108:111]
	v_mfma_f32_16x16x32_bf16 v[180:183], v[20:23], v[196:199], v[180:183]
	v_mfma_f32_16x16x32_bf16 v[164:167], v[28:31], v[196:199], v[164:167]
	v_mfma_f32_16x16x32_bf16 v[148:151], v[20:23], v[204:207], v[148:151]
	v_mfma_f32_16x16x32_bf16 v[140:143], v[28:31], v[204:207], v[140:143]
	v_mfma_f32_16x16x32_bf16 v[132:135], v[20:23], v[224:227], v[132:135]
	v_mfma_f32_16x16x32_bf16 v[124:127], v[28:31], v[224:227], v[124:127]
	s_waitcnt lgkmcnt(0)
	v_mfma_f32_16x16x32_bf16 v[116:119], v[20:23], v[246:249], v[116:119]
	v_mfma_f32_16x16x32_bf16 v[108:111], v[28:31], v[246:249], v[108:111]
	v_mfma_f32_16x16x32_bf16 v[172:175], v[152:155], v[192:195], v[172:175]
	v_mfma_f32_16x16x32_bf16 v[156:159], v[168:171], v[192:195], v[156:159]
	v_mfma_f32_16x16x32_bf16 v[144:147], v[152:155], v[200:203], v[144:147]
	v_mfma_f32_16x16x32_bf16 v[136:139], v[168:171], v[200:203], v[136:139]
	v_mfma_f32_16x16x32_bf16 v[128:131], v[152:155], v[220:223], v[128:131]
	v_mfma_f32_16x16x32_bf16 v[120:123], v[168:171], v[220:223], v[120:123]
	v_mfma_f32_16x16x32_bf16 v[112:115], v[152:155], v[228:231], v[112:115]
	v_mfma_f32_16x16x32_bf16 v[104:107], v[168:171], v[228:231], v[104:107]
	v_mfma_f32_16x16x32_bf16 v[172:175], v[160:163], v[196:199], v[172:175]
	v_mfma_f32_16x16x32_bf16 v[156:159], v[176:179], v[196:199], v[156:159]
	v_mfma_f32_16x16x32_bf16 v[144:147], v[160:163], v[204:207], v[144:147]
	v_mfma_f32_16x16x32_bf16 v[136:139], v[176:179], v[204:207], v[136:139]
	v_mfma_f32_16x16x32_bf16 v[128:131], v[160:163], v[224:227], v[128:131]
	v_mfma_f32_16x16x32_bf16 v[120:123], v[176:179], v[224:227], v[120:123]
	v_mfma_f32_16x16x32_bf16 v[112:115], v[160:163], v[246:249], v[112:115]
	v_mfma_f32_16x16x32_bf16 v[104:107], v[176:179], v[246:249], v[104:107]
	s_barrier
	ds_read_b128 v[192:195], v245 offset:16384
	ds_read_b128 v[196:199], v245 offset:17408
	ds_read_b128 v[200:203], v245 offset:18432
	ds_read_b128 v[204:207], v245 offset:19456
	ds_read_b128 v[220:223], v245 offset:20480
	ds_read_b128 v[224:227], v245 offset:21504
	ds_read_b128 v[228:231], v245 offset:22528
	ds_read_b128 v[246:249], v245 offset:23552
	s_mov_b32 m0, s51
	s_nop 0
	buffer_load_dwordx4 v242, s[56:59], s16 offen lds
	s_add_i32 s18, s16, 0x80000
	s_mov_b32 m0, s52
	s_nop 0
	buffer_load_dwordx4 v243, s[56:59], s16 offen lds
	s_nop 0
	s_mov_b32 m0, s53
	s_nop 0
	buffer_load_dwordx4 v242, s[56:59], s18 offen lds
	s_nop 0
	s_mov_b32 m0, s55
	s_nop 0
	buffer_load_dwordx4 v243, s[56:59], s18 offen lds
	s_nop 0
	s_mov_b32 m0, s31
	s_nop 0
	buffer_load_dwordx4 v242, s[24:27], s17 offen lds
	s_nop 0
	s_mov_b32 m0, s68
	s_nop 0
	buffer_load_dwordx4 v243, s[24:27], s17 offen lds
	s_waitcnt vmcnt(8) lgkmcnt(0)
	s_barrier
	s_waitcnt lgkmcnt(7)
	v_mfma_f32_16x16x32_bf16 v[76:79], v[16:19], v[192:195], v[76:79]
	v_mfma_f32_16x16x32_bf16 v[68:71], v[24:27], v[192:195], v[68:71]
	s_waitcnt lgkmcnt(5)
	v_mfma_f32_16x16x32_bf16 v[60:63], v[16:19], v[200:203], v[60:63]
	v_mfma_f32_16x16x32_bf16 v[52:55], v[24:27], v[200:203], v[52:55]
	s_waitcnt lgkmcnt(3)
	v_mfma_f32_16x16x32_bf16 v[44:47], v[16:19], v[220:223], v[44:47]
	v_mfma_f32_16x16x32_bf16 v[36:39], v[24:27], v[220:223], v[36:39]
	s_waitcnt lgkmcnt(1)
	v_mfma_f32_16x16x32_bf16 v[12:15], v[16:19], v[228:231], v[12:15]
	v_mfma_f32_16x16x32_bf16 v[4:7], v[24:27], v[228:231], v[4:7]
	v_mfma_f32_16x16x32_bf16 v[76:79], v[20:23], v[196:199], v[76:79]
	v_mfma_f32_16x16x32_bf16 v[68:71], v[28:31], v[196:199], v[68:71]
	v_mfma_f32_16x16x32_bf16 v[60:63], v[20:23], v[204:207], v[60:63]
	v_mfma_f32_16x16x32_bf16 v[52:55], v[28:31], v[204:207], v[52:55]
	v_mfma_f32_16x16x32_bf16 v[44:47], v[20:23], v[224:227], v[44:47]
	v_mfma_f32_16x16x32_bf16 v[36:39], v[28:31], v[224:227], v[36:39]
	s_waitcnt lgkmcnt(0)
	v_mfma_f32_16x16x32_bf16 v[12:15], v[20:23], v[246:249], v[12:15]
	v_mfma_f32_16x16x32_bf16 v[4:7], v[28:31], v[246:249], v[4:7]
	v_mfma_f32_16x16x32_bf16 v[40:43], v[152:155], v[220:223], v[40:43]
	v_mfma_f32_16x16x32_bf16 v[32:35], v[168:171], v[220:223], v[32:35]
	v_mfma_f32_16x16x32_bf16 v[8:11], v[152:155], v[228:231], v[8:11]
	v_mfma_f32_16x16x32_bf16 v[0:3], v[168:171], v[228:231], v[0:3]
	v_mfma_f32_16x16x32_bf16 v[16:19], v[152:155], v[192:195], v[72:75]
	v_mfma_f32_16x16x32_bf16 v[20:23], v[168:171], v[192:195], v[64:67]
	v_mfma_f32_16x16x32_bf16 v[24:27], v[152:155], v[200:203], v[56:59]
	v_mfma_f32_16x16x32_bf16 v[28:31], v[168:171], v[200:203], v[48:51]
	v_mfma_f32_16x16x32_bf16 v[40:43], v[160:163], v[224:227], v[40:43]
	v_mfma_f32_16x16x32_bf16 v[32:35], v[176:179], v[224:227], v[32:35]
	v_mfma_f32_16x16x32_bf16 v[8:11], v[160:163], v[246:249], v[8:11]
	v_mfma_f32_16x16x32_bf16 v[0:3], v[176:179], v[246:249], v[0:3]
	v_mfma_f32_16x16x32_bf16 v[16:19], v[160:163], v[196:199], v[16:19]
	v_mfma_f32_16x16x32_bf16 v[20:23], v[176:179], v[196:199], v[20:23]
	v_mfma_f32_16x16x32_bf16 v[24:27], v[160:163], v[204:207], v[24:27]
	v_mfma_f32_16x16x32_bf16 v[28:31], v[176:179], v[204:207], v[28:31]
	s_barrier
	v_add_u32_e32 v72, 0x18000, v83
	v_add_u32_e32 v80, 0x1c000, v83
	ds_read_b128 v[48:51], v72
	ds_read_b128 v[56:59], v72 offset:1024
	ds_read_b128 v[64:67], v72 offset:2048
	ds_read_b128 v[72:75], v72 offset:3072
	ds_read_b128 v[152:155], v80
	ds_read_b128 v[160:163], v80 offset:1024
	ds_read_b128 v[168:171], v80 offset:2048
	ds_read_b128 v[176:179], v80 offset:3072
	ds_read_b128 v[192:195], v245 offset:32768
	ds_read_b128 v[196:199], v245 offset:33792
	ds_read_b128 v[200:203], v245 offset:34816
	ds_read_b128 v[204:207], v245 offset:35840
	ds_read_b128 v[220:223], v245 offset:36864
	ds_read_b128 v[224:227], v245 offset:37888
	ds_read_b128 v[228:231], v245 offset:38912
	ds_read_b128 v[246:249], v245 offset:39936
	s_add_i32 s17, s17, 0x80000
	s_mov_b32 m0, s69
	s_nop 0
	buffer_load_dwordx4 v242, s[24:27], s17 offen lds
	s_nop 0
	s_mov_b32 m0, s70
	s_nop 0
	buffer_load_dwordx4 v243, s[24:27], s17 offen lds
	s_waitcnt vmcnt(8) lgkmcnt(0)
	s_barrier
	s_waitcnt lgkmcnt(7)
	v_mfma_f32_16x16x32_bf16 v[180:183], v[48:51], v[192:195], v[180:183]
	v_mfma_f32_16x16x32_bf16 v[164:167], v[64:67], v[192:195], v[164:167]
	s_waitcnt lgkmcnt(5)
	v_mfma_f32_16x16x32_bf16 v[148:151], v[48:51], v[200:203], v[148:151]
	v_mfma_f32_16x16x32_bf16 v[140:143], v[64:67], v[200:203], v[140:143]
	s_waitcnt lgkmcnt(3)
	v_mfma_f32_16x16x32_bf16 v[132:135], v[48:51], v[220:223], v[132:135]
	v_mfma_f32_16x16x32_bf16 v[124:127], v[64:67], v[220:223], v[124:127]
	s_waitcnt lgkmcnt(1)
	v_mfma_f32_16x16x32_bf16 v[116:119], v[48:51], v[228:231], v[116:119]
	v_mfma_f32_16x16x32_bf16 v[108:111], v[64:67], v[228:231], v[108:111]
	v_mfma_f32_16x16x32_bf16 v[180:183], v[56:59], v[196:199], v[180:183]
	v_mfma_f32_16x16x32_bf16 v[164:167], v[72:75], v[196:199], v[164:167]
	v_mfma_f32_16x16x32_bf16 v[148:151], v[56:59], v[204:207], v[148:151]
	v_mfma_f32_16x16x32_bf16 v[140:143], v[72:75], v[204:207], v[140:143]
	v_mfma_f32_16x16x32_bf16 v[132:135], v[56:59], v[224:227], v[132:135]
	v_mfma_f32_16x16x32_bf16 v[124:127], v[72:75], v[224:227], v[124:127]
	s_waitcnt lgkmcnt(0)
	v_mfma_f32_16x16x32_bf16 v[116:119], v[56:59], v[246:249], v[116:119]
	v_mfma_f32_16x16x32_bf16 v[108:111], v[72:75], v[246:249], v[108:111]
	v_mfma_f32_16x16x32_bf16 v[172:175], v[152:155], v[192:195], v[172:175]
	v_mfma_f32_16x16x32_bf16 v[156:159], v[168:171], v[192:195], v[156:159]
	v_mfma_f32_16x16x32_bf16 v[144:147], v[152:155], v[200:203], v[144:147]
	v_mfma_f32_16x16x32_bf16 v[136:139], v[168:171], v[200:203], v[136:139]
	v_mfma_f32_16x16x32_bf16 v[128:131], v[152:155], v[220:223], v[128:131]
	v_mfma_f32_16x16x32_bf16 v[120:123], v[168:171], v[220:223], v[120:123]
	v_mfma_f32_16x16x32_bf16 v[112:115], v[152:155], v[228:231], v[112:115]
	v_mfma_f32_16x16x32_bf16 v[104:107], v[168:171], v[228:231], v[104:107]
	v_mfma_f32_16x16x32_bf16 v[172:175], v[160:163], v[196:199], v[172:175]
	v_mfma_f32_16x16x32_bf16 v[156:159], v[176:179], v[196:199], v[156:159]
	v_mfma_f32_16x16x32_bf16 v[144:147], v[160:163], v[204:207], v[144:147]
	v_mfma_f32_16x16x32_bf16 v[136:139], v[176:179], v[204:207], v[136:139]
	v_mfma_f32_16x16x32_bf16 v[128:131], v[160:163], v[224:227], v[128:131]
	v_mfma_f32_16x16x32_bf16 v[120:123], v[176:179], v[224:227], v[120:123]
	v_mfma_f32_16x16x32_bf16 v[112:115], v[160:163], v[246:249], v[112:115]
	v_mfma_f32_16x16x32_bf16 v[104:107], v[176:179], v[246:249], v[104:107]
	s_barrier
	ds_read_b128 v[192:195], v245 offset:49152
	ds_read_b128 v[196:199], v245 offset:50176
	ds_read_b128 v[200:203], v245 offset:51200
	ds_read_b128 v[204:207], v245 offset:52224
	ds_read_b128 v[220:223], v245 offset:53248
	ds_read_b128 v[224:227], v245 offset:54272
	ds_read_b128 v[228:231], v245 offset:55296
	ds_read_b128 v[246:249], v245 offset:56320
	s_or_b32 s17, s16, 0x4000
	s_mov_b32 m0, s73
	s_nop 0
	buffer_load_dwordx4 v242, s[56:59], s17 offen lds
	s_add_i32 s16, s16, 0x84000
	s_mov_b32 m0, s74
	s_nop 0
	buffer_load_dwordx4 v243, s[56:59], s17 offen lds
	s_nop 0
	s_mov_b32 m0, s77
	s_nop 0
	buffer_load_dwordx4 v242, s[56:59], s16 offen lds
	s_nop 0
	s_mov_b32 m0, s78
	s_nop 0
	buffer_load_dwordx4 v243, s[56:59], s16 offen lds
	s_nop 0
	s_mov_b32 m0, s75
	s_nop 0
	buffer_load_dwordx4 v242, s[24:27], s7 offen lds
	s_nop 0
	s_mov_b32 m0, s76
	s_nop 0
	buffer_load_dwordx4 v243, s[24:27], s7 offen lds
	s_waitcnt vmcnt(8) lgkmcnt(0)
	s_barrier
	s_waitcnt lgkmcnt(7)
	v_mfma_f32_16x16x32_bf16 v[76:79], v[48:51], v[192:195], v[76:79]
	v_mfma_f32_16x16x32_bf16 v[68:71], v[64:67], v[192:195], v[68:71]
	s_waitcnt lgkmcnt(5)
	v_mfma_f32_16x16x32_bf16 v[60:63], v[48:51], v[200:203], v[60:63]
	v_mfma_f32_16x16x32_bf16 v[52:55], v[64:67], v[200:203], v[52:55]
	s_waitcnt lgkmcnt(3)
	v_mfma_f32_16x16x32_bf16 v[44:47], v[48:51], v[220:223], v[44:47]
	v_mfma_f32_16x16x32_bf16 v[36:39], v[64:67], v[220:223], v[36:39]
	s_waitcnt lgkmcnt(1)
	v_mfma_f32_16x16x32_bf16 v[12:15], v[48:51], v[228:231], v[12:15]
	v_mfma_f32_16x16x32_bf16 v[4:7], v[64:67], v[228:231], v[4:7]
	v_mfma_f32_16x16x32_bf16 v[76:79], v[56:59], v[196:199], v[76:79]
	v_mfma_f32_16x16x32_bf16 v[68:71], v[72:75], v[196:199], v[68:71]
	v_mfma_f32_16x16x32_bf16 v[60:63], v[56:59], v[204:207], v[60:63]
	v_mfma_f32_16x16x32_bf16 v[52:55], v[72:75], v[204:207], v[52:55]
	v_mfma_f32_16x16x32_bf16 v[44:47], v[56:59], v[224:227], v[44:47]
	v_mfma_f32_16x16x32_bf16 v[36:39], v[72:75], v[224:227], v[36:39]
	s_waitcnt lgkmcnt(0)
	v_mfma_f32_16x16x32_bf16 v[12:15], v[56:59], v[246:249], v[12:15]
	v_mfma_f32_16x16x32_bf16 v[4:7], v[72:75], v[246:249], v[4:7]
	v_mfma_f32_16x16x32_bf16 v[16:19], v[152:155], v[192:195], v[16:19]
	v_mfma_f32_16x16x32_bf16 v[72:75], v[160:163], v[196:199], v[16:19]
	v_mfma_f32_16x16x32_bf16 v[16:19], v[168:171], v[192:195], v[20:23]
	v_mfma_f32_16x16x32_bf16 v[64:67], v[176:179], v[196:199], v[16:19]
	v_mfma_f32_16x16x32_bf16 v[16:19], v[152:155], v[200:203], v[24:27]
	v_mfma_f32_16x16x32_bf16 v[56:59], v[160:163], v[204:207], v[16:19]
	v_mfma_f32_16x16x32_bf16 v[16:19], v[168:171], v[200:203], v[28:31]
	v_mfma_f32_16x16x32_bf16 v[48:51], v[176:179], v[204:207], v[16:19]
	v_mfma_f32_16x16x32_bf16 v[16:19], v[152:155], v[220:223], v[40:43]
	v_mfma_f32_16x16x32_bf16 v[40:43], v[160:163], v[224:227], v[16:19]
	v_mfma_f32_16x16x32_bf16 v[16:19], v[168:171], v[220:223], v[32:35]
	v_mfma_f32_16x16x32_bf16 v[8:11], v[152:155], v[228:231], v[8:11]
	v_mfma_f32_16x16x32_bf16 v[0:3], v[168:171], v[228:231], v[0:3]
	v_mfma_f32_16x16x32_bf16 v[32:35], v[176:179], v[224:227], v[16:19]
	v_mfma_f32_16x16x32_bf16 v[8:11], v[160:163], v[246:249], v[8:11]
	v_mfma_f32_16x16x32_bf16 v[0:3], v[176:179], v[246:249], v[0:3]
	s_barrier
	s_add_i32 s6, s6, 2
	s_add_i32 s4, s4, 0x8000
	s_add_i32 s5, s5, 0x8000
	s_cmp_gt_u32 s6, 29
	s_cbranch_scc0 .LBB0_143

.LBB0_594:
	v_add_u32_e32 v80, 0x10000, v226
	ds_read_b128 v[152:155], v80
	ds_read_b128 v[156:159], v80 offset:1024
	ds_read_b128 v[160:163], v80 offset:2048
	ds_read_b128 v[164:167], v80 offset:3072
	v_add_u32_e32 v80, 0x14000, v226
	ds_read_b128 v[168:171], v80
	ds_read_b128 v[172:175], v80 offset:1024
	ds_read_b128 v[176:179], v80 offset:2048
	ds_read_b128 v[180:183], v80 offset:3072
	s_add_i32 s97, s96, s39
	s_add_i32 s94, s97, 0x8000
	s_add_i32 s95, s93, s39
	s_cmp_eq_u32 s39, 0x78000
	s_cselect_b32 s36, vcc_lo, s94
	s_cselect_b32 s95, vcc_hi, s95
	s_or_b32 s94, s36, 0x4000
	ds_read_b128 v[184:187], v227
	ds_read_b128 v[188:191], v227 offset:1024
	ds_read_b128 v[192:195], v227 offset:2048
	ds_read_b128 v[196:199], v227 offset:3072
	ds_read_b128 v[200:203], v227 offset:4096
	ds_read_b128 v[204:207], v227 offset:5120
	ds_read_b128 v[228:231], v227 offset:6144
	ds_read_b128 v[240:243], v227 offset:7168
	s_add_i32 s97, s97, 0x84000
	s_mov_b32 m0, s85
	s_nop 0
	buffer_load_dwordx4 v224, s[60:63], s97 offen lds
	s_nop 0
	s_mov_b32 m0, s86
	s_nop 0
	buffer_load_dwordx4 v225, s[60:63], s97 offen lds
	s_waitcnt vmcnt(8) lgkmcnt(0)
	s_barrier
	s_waitcnt lgkmcnt(7)
	v_mfma_f32_16x16x32_bf16 v[148:151], v[152:155], v[184:187], v[148:151]
	v_mfma_f32_16x16x32_bf16 v[144:147], v[160:163], v[184:187], v[144:147]
	s_waitcnt lgkmcnt(5)
	v_mfma_f32_16x16x32_bf16 v[132:135], v[152:155], v[192:195], v[132:135]
	v_mfma_f32_16x16x32_bf16 v[128:131], v[160:163], v[192:195], v[128:131]
	s_waitcnt lgkmcnt(3)
	v_mfma_f32_16x16x32_bf16 v[116:119], v[152:155], v[200:203], v[116:119]
	v_mfma_f32_16x16x32_bf16 v[112:115], v[160:163], v[200:203], v[112:115]
	s_waitcnt lgkmcnt(1)
	v_mfma_f32_16x16x32_bf16 v[76:79], v[152:155], v[228:231], v[76:79]
	v_mfma_f32_16x16x32_bf16 v[72:75], v[160:163], v[228:231], v[72:75]
	v_mfma_f32_16x16x32_bf16 v[148:151], v[156:159], v[188:191], v[148:151]
	v_mfma_f32_16x16x32_bf16 v[144:147], v[164:167], v[188:191], v[144:147]
	v_mfma_f32_16x16x32_bf16 v[132:135], v[156:159], v[196:199], v[132:135]
	v_mfma_f32_16x16x32_bf16 v[128:131], v[164:167], v[196:199], v[128:131]
	v_mfma_f32_16x16x32_bf16 v[116:119], v[156:159], v[204:207], v[116:119]
	v_mfma_f32_16x16x32_bf16 v[112:115], v[164:167], v[204:207], v[112:115]
	s_waitcnt lgkmcnt(0)
	v_mfma_f32_16x16x32_bf16 v[76:79], v[156:159], v[240:243], v[76:79]
	v_mfma_f32_16x16x32_bf16 v[72:75], v[164:167], v[240:243], v[72:75]
	v_mfma_f32_16x16x32_bf16 v[140:143], v[168:171], v[184:187], v[140:143]
	v_mfma_f32_16x16x32_bf16 v[136:139], v[176:179], v[184:187], v[136:139]
	v_mfma_f32_16x16x32_bf16 v[124:127], v[168:171], v[192:195], v[124:127]
	v_mfma_f32_16x16x32_bf16 v[120:123], v[176:179], v[192:195], v[120:123]
	v_mfma_f32_16x16x32_bf16 v[108:111], v[168:171], v[200:203], v[108:111]
	v_mfma_f32_16x16x32_bf16 v[104:107], v[176:179], v[200:203], v[104:107]
	v_mfma_f32_16x16x32_bf16 v[68:71], v[168:171], v[228:231], v[68:71]
	v_mfma_f32_16x16x32_bf16 v[64:67], v[176:179], v[228:231], v[64:67]
	v_mfma_f32_16x16x32_bf16 v[140:143], v[172:175], v[188:191], v[140:143]
	v_mfma_f32_16x16x32_bf16 v[136:139], v[180:183], v[188:191], v[136:139]
	v_mfma_f32_16x16x32_bf16 v[124:127], v[172:175], v[196:199], v[124:127]
	v_mfma_f32_16x16x32_bf16 v[120:123], v[180:183], v[196:199], v[120:123]
	v_mfma_f32_16x16x32_bf16 v[108:111], v[172:175], v[204:207], v[108:111]
	v_mfma_f32_16x16x32_bf16 v[104:107], v[180:183], v[204:207], v[104:107]
	v_mfma_f32_16x16x32_bf16 v[68:71], v[172:175], v[240:243], v[68:71]
	v_mfma_f32_16x16x32_bf16 v[64:67], v[180:183], v[240:243], v[64:67]
	s_barrier
	ds_read_b128 v[184:187], v227 offset:16384
	ds_read_b128 v[188:191], v227 offset:17408
	ds_read_b128 v[192:195], v227 offset:18432
	ds_read_b128 v[196:199], v227 offset:19456
	ds_read_b128 v[200:203], v227 offset:20480
	ds_read_b128 v[204:207], v227 offset:21504
	ds_read_b128 v[228:231], v227 offset:22528
	ds_read_b128 v[240:243], v227 offset:23552
	s_mov_b32 m0, s34
	s_nop 0
	buffer_load_dwordx4 v224, s[48:51], s95 offen lds
	s_add_i32 s97, s95, 0x80000
	s_mov_b32 m0, s55
	s_nop 0
	buffer_load_dwordx4 v225, s[48:51], s95 offen lds
	s_nop 0
	s_mov_b32 m0, s72
	s_nop 0
	buffer_load_dwordx4 v224, s[48:51], s97 offen lds
	s_nop 0
	s_mov_b32 m0, s73
	s_nop 0
	buffer_load_dwordx4 v225, s[48:51], s97 offen lds
	s_nop 0
	s_mov_b32 m0, s31
	s_nop 0
	buffer_load_dwordx4 v224, s[60:63], s36 offen lds
	s_nop 0
	s_mov_b32 m0, s74
	s_nop 0
	buffer_load_dwordx4 v225, s[60:63], s36 offen lds
	s_waitcnt vmcnt(8) lgkmcnt(0)
	s_barrier
	s_waitcnt lgkmcnt(7)
	v_mfma_f32_16x16x32_bf16 v[60:63], v[152:155], v[184:187], v[60:63]
	v_mfma_f32_16x16x32_bf16 v[56:59], v[160:163], v[184:187], v[56:59]
	s_waitcnt lgkmcnt(5)
	v_mfma_f32_16x16x32_bf16 v[44:47], v[152:155], v[192:195], v[44:47]
	v_mfma_f32_16x16x32_bf16 v[40:43], v[160:163], v[192:195], v[40:43]
	s_waitcnt lgkmcnt(3)
	v_mfma_f32_16x16x32_bf16 v[28:31], v[152:155], v[200:203], v[28:31]
	v_mfma_f32_16x16x32_bf16 v[24:27], v[160:163], v[200:203], v[24:27]
	s_waitcnt lgkmcnt(1)
	v_mfma_f32_16x16x32_bf16 v[12:15], v[152:155], v[228:231], v[12:15]
	v_mfma_f32_16x16x32_bf16 v[8:11], v[160:163], v[228:231], v[8:11]
	v_mfma_f32_16x16x32_bf16 v[60:63], v[156:159], v[188:191], v[60:63]
	v_mfma_f32_16x16x32_bf16 v[56:59], v[164:167], v[188:191], v[56:59]
	v_mfma_f32_16x16x32_bf16 v[44:47], v[156:159], v[196:199], v[44:47]
	v_mfma_f32_16x16x32_bf16 v[40:43], v[164:167], v[196:199], v[40:43]
	v_mfma_f32_16x16x32_bf16 v[28:31], v[156:159], v[204:207], v[28:31]
	v_mfma_f32_16x16x32_bf16 v[24:27], v[164:167], v[204:207], v[24:27]
	s_waitcnt lgkmcnt(0)
	v_mfma_f32_16x16x32_bf16 v[12:15], v[156:159], v[240:243], v[12:15]
	v_mfma_f32_16x16x32_bf16 v[8:11], v[164:167], v[240:243], v[8:11]
	v_mfma_f32_16x16x32_bf16 v[52:55], v[168:171], v[184:187], v[52:55]
	v_mfma_f32_16x16x32_bf16 v[48:51], v[176:179], v[184:187], v[48:51]
	v_mfma_f32_16x16x32_bf16 v[36:39], v[168:171], v[192:195], v[36:39]
	v_mfma_f32_16x16x32_bf16 v[32:35], v[176:179], v[192:195], v[32:35]
	v_mfma_f32_16x16x32_bf16 v[20:23], v[168:171], v[200:203], v[20:23]
	v_mfma_f32_16x16x32_bf16 v[16:19], v[176:179], v[200:203], v[16:19]
	v_mfma_f32_16x16x32_bf16 v[4:7], v[168:171], v[228:231], v[4:7]
	v_mfma_f32_16x16x32_bf16 v[0:3], v[176:179], v[228:231], v[0:3]
	v_mfma_f32_16x16x32_bf16 v[52:55], v[172:175], v[188:191], v[52:55]
	v_mfma_f32_16x16x32_bf16 v[48:51], v[180:183], v[188:191], v[48:51]
	v_mfma_f32_16x16x32_bf16 v[36:39], v[172:175], v[196:199], v[36:39]
	v_mfma_f32_16x16x32_bf16 v[32:35], v[180:183], v[196:199], v[32:35]
	v_mfma_f32_16x16x32_bf16 v[20:23], v[172:175], v[204:207], v[20:23]
	v_mfma_f32_16x16x32_bf16 v[16:19], v[180:183], v[204:207], v[16:19]
	v_mfma_f32_16x16x32_bf16 v[4:7], v[172:175], v[240:243], v[4:7]
	v_mfma_f32_16x16x32_bf16 v[0:3], v[180:183], v[240:243], v[0:3]
	s_barrier
	v_add_u32_e32 v80, 0x18000, v226
	ds_read_b128 v[152:155], v80
	ds_read_b128 v[156:159], v80 offset:1024
	ds_read_b128 v[160:163], v80 offset:2048
	ds_read_b128 v[164:167], v80 offset:3072
	v_add_u32_e32 v80, 0x1c000, v226
	ds_read_b128 v[168:171], v80
	ds_read_b128 v[172:175], v80 offset:1024
	ds_read_b128 v[176:179], v80 offset:2048
	ds_read_b128 v[180:183], v80 offset:3072
	ds_read_b128 v[184:187], v227 offset:32768
	ds_read_b128 v[188:191], v227 offset:33792
	ds_read_b128 v[192:195], v227 offset:34816
	ds_read_b128 v[196:199], v227 offset:35840
	ds_read_b128 v[200:203], v227 offset:36864
	ds_read_b128 v[204:207], v227 offset:37888
	ds_read_b128 v[228:231], v227 offset:38912
	ds_read_b128 v[240:243], v227 offset:39936
	s_add_i32 s36, s36, 0x80000
	s_mov_b32 m0, s75
	s_nop 0
	buffer_load_dwordx4 v224, s[60:63], s36 offen lds
	s_nop 0
	s_mov_b32 m0, s76
	s_nop 0
	buffer_load_dwordx4 v225, s[60:63], s36 offen lds
	s_waitcnt vmcnt(8) lgkmcnt(0)
	s_barrier
	s_waitcnt lgkmcnt(7)
	v_mfma_f32_16x16x32_bf16 v[148:151], v[152:155], v[184:187], v[148:151]
	v_mfma_f32_16x16x32_bf16 v[144:147], v[160:163], v[184:187], v[144:147]
	s_waitcnt lgkmcnt(5)
	v_mfma_f32_16x16x32_bf16 v[132:135], v[152:155], v[192:195], v[132:135]
	v_mfma_f32_16x16x32_bf16 v[128:131], v[160:163], v[192:195], v[128:131]
	s_waitcnt lgkmcnt(3)
	v_mfma_f32_16x16x32_bf16 v[116:119], v[152:155], v[200:203], v[116:119]
	v_mfma_f32_16x16x32_bf16 v[112:115], v[160:163], v[200:203], v[112:115]
	s_waitcnt lgkmcnt(1)
	v_mfma_f32_16x16x32_bf16 v[76:79], v[152:155], v[228:231], v[76:79]
	v_mfma_f32_16x16x32_bf16 v[72:75], v[160:163], v[228:231], v[72:75]
	v_mfma_f32_16x16x32_bf16 v[148:151], v[156:159], v[188:191], v[148:151]
	v_mfma_f32_16x16x32_bf16 v[144:147], v[164:167], v[188:191], v[144:147]
	v_mfma_f32_16x16x32_bf16 v[132:135], v[156:159], v[196:199], v[132:135]
	v_mfma_f32_16x16x32_bf16 v[128:131], v[164:167], v[196:199], v[128:131]
	v_mfma_f32_16x16x32_bf16 v[116:119], v[156:159], v[204:207], v[116:119]
	v_mfma_f32_16x16x32_bf16 v[112:115], v[164:167], v[204:207], v[112:115]
	s_waitcnt lgkmcnt(0)
	v_mfma_f32_16x16x32_bf16 v[76:79], v[156:159], v[240:243], v[76:79]
	v_mfma_f32_16x16x32_bf16 v[72:75], v[164:167], v[240:243], v[72:75]
	v_mfma_f32_16x16x32_bf16 v[140:143], v[168:171], v[184:187], v[140:143]
	v_mfma_f32_16x16x32_bf16 v[136:139], v[176:179], v[184:187], v[136:139]
	v_mfma_f32_16x16x32_bf16 v[124:127], v[168:171], v[192:195], v[124:127]
	v_mfma_f32_16x16x32_bf16 v[120:123], v[176:179], v[192:195], v[120:123]
	v_mfma_f32_16x16x32_bf16 v[108:111], v[168:171], v[200:203], v[108:111]
	v_mfma_f32_16x16x32_bf16 v[104:107], v[176:179], v[200:203], v[104:107]
	v_mfma_f32_16x16x32_bf16 v[68:71], v[168:171], v[228:231], v[68:71]
	v_mfma_f32_16x16x32_bf16 v[64:67], v[176:179], v[228:231], v[64:67]
	v_mfma_f32_16x16x32_bf16 v[140:143], v[172:175], v[188:191], v[140:143]
	v_mfma_f32_16x16x32_bf16 v[136:139], v[180:183], v[188:191], v[136:139]
	v_mfma_f32_16x16x32_bf16 v[124:127], v[172:175], v[196:199], v[124:127]
	v_mfma_f32_16x16x32_bf16 v[120:123], v[180:183], v[196:199], v[120:123]
	v_mfma_f32_16x16x32_bf16 v[108:111], v[172:175], v[204:207], v[108:111]
	v_mfma_f32_16x16x32_bf16 v[104:107], v[180:183], v[204:207], v[104:107]
	v_mfma_f32_16x16x32_bf16 v[68:71], v[172:175], v[240:243], v[68:71]
	v_mfma_f32_16x16x32_bf16 v[64:67], v[180:183], v[240:243], v[64:67]
	s_barrier
	ds_read_b128 v[184:187], v227 offset:49152
	ds_read_b128 v[188:191], v227 offset:50176
	ds_read_b128 v[192:195], v227 offset:51200
	ds_read_b128 v[196:199], v227 offset:52224
	ds_read_b128 v[200:203], v227 offset:53248
	ds_read_b128 v[204:207], v227 offset:54272
	ds_read_b128 v[228:231], v227 offset:55296
	ds_read_b128 v[240:243], v227 offset:56320
	s_or_b32 s36, s95, 0x4000
	s_mov_b32 m0, s77
	s_nop 0
	buffer_load_dwordx4 v224, s[48:51], s36 offen lds
	s_nop 0
	s_mov_b32 m0, s78
	s_nop 0
	buffer_load_dwordx4 v225, s[48:51], s36 offen lds
	s_add_i32 s36, s95, 0x84000
	s_mov_b32 m0, s83
	s_nop 0
	buffer_load_dwordx4 v224, s[48:51], s36 offen lds
	s_nop 0
	s_mov_b32 m0, s84
	s_nop 0
	buffer_load_dwordx4 v225, s[48:51], s36 offen lds
	s_nop 0
	s_mov_b32 m0, s79
	s_nop 0
	buffer_load_dwordx4 v224, s[60:63], s94 offen lds
	s_nop 0
	s_mov_b32 m0, s82
	s_nop 0
	buffer_load_dwordx4 v225, s[60:63], s94 offen lds
	s_waitcnt vmcnt(8) lgkmcnt(0)
	s_barrier
	s_waitcnt lgkmcnt(7)
	v_mfma_f32_16x16x32_bf16 v[60:63], v[152:155], v[184:187], v[60:63]
	v_mfma_f32_16x16x32_bf16 v[56:59], v[160:163], v[184:187], v[56:59]
	s_waitcnt lgkmcnt(5)
	v_mfma_f32_16x16x32_bf16 v[44:47], v[152:155], v[192:195], v[44:47]
	v_mfma_f32_16x16x32_bf16 v[40:43], v[160:163], v[192:195], v[40:43]
	s_waitcnt lgkmcnt(3)
	v_mfma_f32_16x16x32_bf16 v[28:31], v[152:155], v[200:203], v[28:31]
	v_mfma_f32_16x16x32_bf16 v[24:27], v[160:163], v[200:203], v[24:27]
	s_waitcnt lgkmcnt(1)
	v_mfma_f32_16x16x32_bf16 v[12:15], v[152:155], v[228:231], v[12:15]
	v_mfma_f32_16x16x32_bf16 v[8:11], v[160:163], v[228:231], v[8:11]
	v_mfma_f32_16x16x32_bf16 v[60:63], v[156:159], v[188:191], v[60:63]
	v_mfma_f32_16x16x32_bf16 v[56:59], v[164:167], v[188:191], v[56:59]
	v_mfma_f32_16x16x32_bf16 v[44:47], v[156:159], v[196:199], v[44:47]
	v_mfma_f32_16x16x32_bf16 v[40:43], v[164:167], v[196:199], v[40:43]
	v_mfma_f32_16x16x32_bf16 v[28:31], v[156:159], v[204:207], v[28:31]
	v_mfma_f32_16x16x32_bf16 v[24:27], v[164:167], v[204:207], v[24:27]
	s_waitcnt lgkmcnt(0)
	v_mfma_f32_16x16x32_bf16 v[12:15], v[156:159], v[240:243], v[12:15]
	v_mfma_f32_16x16x32_bf16 v[8:11], v[164:167], v[240:243], v[8:11]
	v_mfma_f32_16x16x32_bf16 v[52:55], v[168:171], v[184:187], v[52:55]
	v_mfma_f32_16x16x32_bf16 v[48:51], v[176:179], v[184:187], v[48:51]
	v_mfma_f32_16x16x32_bf16 v[36:39], v[168:171], v[192:195], v[36:39]
	v_mfma_f32_16x16x32_bf16 v[32:35], v[176:179], v[192:195], v[32:35]
	v_mfma_f32_16x16x32_bf16 v[20:23], v[168:171], v[200:203], v[20:23]
	v_mfma_f32_16x16x32_bf16 v[16:19], v[176:179], v[200:203], v[16:19]
	v_mfma_f32_16x16x32_bf16 v[4:7], v[168:171], v[228:231], v[4:7]
	v_mfma_f32_16x16x32_bf16 v[0:3], v[176:179], v[228:231], v[0:3]
	v_mfma_f32_16x16x32_bf16 v[52:55], v[172:175], v[188:191], v[52:55]
	v_mfma_f32_16x16x32_bf16 v[48:51], v[180:183], v[188:191], v[48:51]
	v_mfma_f32_16x16x32_bf16 v[36:39], v[172:175], v[196:199], v[36:39]
	v_mfma_f32_16x16x32_bf16 v[32:35], v[180:183], v[196:199], v[32:35]
	v_mfma_f32_16x16x32_bf16 v[20:23], v[172:175], v[204:207], v[20:23]
	v_mfma_f32_16x16x32_bf16 v[16:19], v[180:183], v[204:207], v[16:19]
	v_mfma_f32_16x16x32_bf16 v[4:7], v[172:175], v[240:243], v[4:7]
	v_mfma_f32_16x16x32_bf16 v[0:3], v[180:183], v[240:243], v[0:3]
	s_barrier
	s_add_i32 s38, s38, 2
	s_add_i32 s39, s39, 0x8000
	s_cmp_gt_u32 s38, 29
	s_cbranch_scc1 .LBB0_597

.Lnb_p4:
	s_add_i32 s11, s8, 0xfff84000
	s_cmp_eq_u32 s10, 28
	s_cselect_b32 s13, s6, s11
	s_cselect_b32 s12, s7, s9
	s_or_b32 s11, s13, 0x4000
	s_mov_b32 m0, s89
	s_nop 0
	buffer_load_dwordx4 v220, s[64:67], s8 offen lds
	s_nop 0
	s_mov_b32 m0, s91
	s_nop 0
	buffer_load_dwordx4 v221, s[64:67], s8 offen lds
	s_waitcnt vmcnt(24) lgkmcnt(0)
	s_barrier
	s_waitcnt lgkmcnt(7)
	v_mfma_f32_16x16x32_bf16 v[164:167], v[128:131], v[184:187], 0
	v_mfma_f32_16x16x32_bf16 v[160:163], v[152:155], v[184:187], 0
	s_waitcnt lgkmcnt(5)
	v_mfma_f32_16x16x32_bf16 v[136:139], v[128:131], v[192:195], 0
	v_mfma_f32_16x16x32_bf16 v[132:135], v[152:155], v[192:195], 0
	s_waitcnt lgkmcnt(3)
	v_mfma_f32_16x16x32_bf16 v[116:119], v[128:131], v[200:203], 0
	v_mfma_f32_16x16x32_bf16 v[112:115], v[152:155], v[200:203], 0
	s_waitcnt lgkmcnt(1)
	v_mfma_f32_16x16x32_bf16 v[76:79], v[128:131], v[224:227], 0
	v_mfma_f32_16x16x32_bf16 v[72:75], v[152:155], v[224:227], 0
	v_mfma_f32_16x16x32_bf16 v[164:167], v[140:143], v[188:191], v[164:167]
	v_mfma_f32_16x16x32_bf16 v[160:163], v[156:159], v[188:191], v[160:163]
	v_mfma_f32_16x16x32_bf16 v[136:139], v[140:143], v[196:199], v[136:139]
	v_mfma_f32_16x16x32_bf16 v[132:135], v[156:159], v[196:199], v[132:135]
	v_mfma_f32_16x16x32_bf16 v[116:119], v[140:143], v[204:207], v[116:119]
	v_mfma_f32_16x16x32_bf16 v[112:115], v[156:159], v[204:207], v[112:115]
	s_waitcnt lgkmcnt(0)
	v_mfma_f32_16x16x32_bf16 v[76:79], v[140:143], v[228:231], v[76:79]
	v_mfma_f32_16x16x32_bf16 v[72:75], v[156:159], v[228:231], v[72:75]
	v_mfma_f32_16x16x32_bf16 v[148:151], v[168:171], v[184:187], 0
	v_mfma_f32_16x16x32_bf16 v[144:147], v[176:179], v[184:187], 0
	v_mfma_f32_16x16x32_bf16 v[124:127], v[168:171], v[192:195], 0
	v_mfma_f32_16x16x32_bf16 v[120:123], v[176:179], v[192:195], 0
	v_mfma_f32_16x16x32_bf16 v[108:111], v[168:171], v[200:203], 0
	v_mfma_f32_16x16x32_bf16 v[104:107], v[176:179], v[200:203], 0
	v_mfma_f32_16x16x32_bf16 v[68:71], v[168:171], v[224:227], 0
	v_mfma_f32_16x16x32_bf16 v[64:67], v[176:179], v[224:227], 0
	v_mfma_f32_16x16x32_bf16 v[148:151], v[172:175], v[188:191], v[148:151]
	v_mfma_f32_16x16x32_bf16 v[144:147], v[180:183], v[188:191], v[144:147]
	v_mfma_f32_16x16x32_bf16 v[124:127], v[172:175], v[196:199], v[124:127]
	v_mfma_f32_16x16x32_bf16 v[120:123], v[180:183], v[196:199], v[120:123]
	v_mfma_f32_16x16x32_bf16 v[108:111], v[172:175], v[204:207], v[108:111]
	v_mfma_f32_16x16x32_bf16 v[104:107], v[180:183], v[204:207], v[104:107]
	v_mfma_f32_16x16x32_bf16 v[68:71], v[172:175], v[228:231], v[68:71]
	v_mfma_f32_16x16x32_bf16 v[64:67], v[180:183], v[228:231], v[64:67]
	s_barrier
	ds_read_b128 v[184:187], v223 offset:16384
	ds_read_b128 v[188:191], v223 offset:17408
	ds_read_b128 v[192:195], v223 offset:18432
	ds_read_b128 v[196:199], v223 offset:19456
	ds_read_b128 v[200:203], v223 offset:20480
	ds_read_b128 v[204:207], v223 offset:21504
	ds_read_b128 v[224:227], v223 offset:22528
	ds_read_b128 v[228:231], v223 offset:23552
	s_mov_b32 m0, s55
	s_nop 0
	buffer_load_dwordx4 v220, s[48:51], s12 offen lds
	s_add_i32 s14, s12, 0x80000
	s_mov_b32 m0, s76
	s_nop 0
	buffer_load_dwordx4 v221, s[48:51], s12 offen lds
	s_nop 0
	s_mov_b32 m0, s77
	s_nop 0
	buffer_load_dwordx4 v220, s[48:51], s14 offen lds
	s_nop 0
	s_mov_b32 m0, s78
	s_nop 0
	buffer_load_dwordx4 v221, s[48:51], s14 offen lds
	s_nop 0
	s_mov_b32 m0, s31
	s_nop 0
	buffer_load_dwordx4 v220, s[64:67], s13 offen lds
	s_nop 0
	s_mov_b32 m0, s79
	s_nop 0
	buffer_load_dwordx4 v221, s[64:67], s13 offen lds
	s_waitcnt vmcnt(24) lgkmcnt(0)
	s_barrier
	s_waitcnt lgkmcnt(7)
	v_mfma_f32_16x16x32_bf16 v[60:63], v[128:131], v[184:187], 0
	v_mfma_f32_16x16x32_bf16 v[56:59], v[152:155], v[184:187], 0
	s_waitcnt lgkmcnt(5)
	v_mfma_f32_16x16x32_bf16 v[44:47], v[128:131], v[192:195], 0
	v_mfma_f32_16x16x32_bf16 v[40:43], v[152:155], v[192:195], 0
	s_waitcnt lgkmcnt(3)
	v_mfma_f32_16x16x32_bf16 v[28:31], v[128:131], v[200:203], 0
	v_mfma_f32_16x16x32_bf16 v[24:27], v[152:155], v[200:203], 0
	s_waitcnt lgkmcnt(1)
	v_mfma_f32_16x16x32_bf16 v[12:15], v[128:131], v[224:227], 0
	v_mfma_f32_16x16x32_bf16 v[8:11], v[152:155], v[224:227], 0
	v_mfma_f32_16x16x32_bf16 v[60:63], v[140:143], v[188:191], v[60:63]
	v_mfma_f32_16x16x32_bf16 v[56:59], v[156:159], v[188:191], v[56:59]
	v_mfma_f32_16x16x32_bf16 v[44:47], v[140:143], v[196:199], v[44:47]
	v_mfma_f32_16x16x32_bf16 v[40:43], v[156:159], v[196:199], v[40:43]
	v_mfma_f32_16x16x32_bf16 v[28:31], v[140:143], v[204:207], v[28:31]
	v_mfma_f32_16x16x32_bf16 v[24:27], v[156:159], v[204:207], v[24:27]
	s_waitcnt lgkmcnt(0)
	v_mfma_f32_16x16x32_bf16 v[12:15], v[140:143], v[228:231], v[12:15]
	v_mfma_f32_16x16x32_bf16 v[8:11], v[156:159], v[228:231], v[8:11]
	v_mfma_f32_16x16x32_bf16 v[52:55], v[168:171], v[184:187], 0
	v_mfma_f32_16x16x32_bf16 v[48:51], v[176:179], v[184:187], 0
	v_mfma_f32_16x16x32_bf16 v[36:39], v[168:171], v[192:195], 0
	v_mfma_f32_16x16x32_bf16 v[32:35], v[176:179], v[192:195], 0
	v_mfma_f32_16x16x32_bf16 v[20:23], v[168:171], v[200:203], 0
	v_mfma_f32_16x16x32_bf16 v[16:19], v[176:179], v[200:203], 0
	v_mfma_f32_16x16x32_bf16 v[4:7], v[168:171], v[224:227], 0
	v_mfma_f32_16x16x32_bf16 v[0:3], v[176:179], v[224:227], 0
	v_mfma_f32_16x16x32_bf16 v[52:55], v[172:175], v[188:191], v[52:55]
	v_mfma_f32_16x16x32_bf16 v[48:51], v[180:183], v[188:191], v[48:51]
	v_mfma_f32_16x16x32_bf16 v[36:39], v[172:175], v[196:199], v[36:39]
	v_mfma_f32_16x16x32_bf16 v[32:35], v[180:183], v[196:199], v[32:35]
	v_mfma_f32_16x16x32_bf16 v[20:23], v[172:175], v[204:207], v[20:23]
	v_mfma_f32_16x16x32_bf16 v[16:19], v[180:183], v[204:207], v[16:19]
	v_mfma_f32_16x16x32_bf16 v[4:7], v[172:175], v[228:231], v[4:7]
	v_mfma_f32_16x16x32_bf16 v[0:3], v[180:183], v[228:231], v[0:3]
	s_barrier
	v_add_u32_e32 v156, 0x18000, v222
	v_add_u32_e32 v180, 0x1c000, v222
	ds_read_b128 v[128:131], v156
	ds_read_b128 v[140:143], v156 offset:1024
	ds_read_b128 v[152:155], v156 offset:2048
	ds_read_b128 v[156:159], v156 offset:3072
	ds_read_b128 v[168:171], v180
	ds_read_b128 v[172:175], v180 offset:1024
	ds_read_b128 v[176:179], v180 offset:2048
	ds_read_b128 v[180:183], v180 offset:3072
	ds_read_b128 v[184:187], v223 offset:32768
	ds_read_b128 v[188:191], v223 offset:33792
	ds_read_b128 v[192:195], v223 offset:34816
	ds_read_b128 v[196:199], v223 offset:35840
	ds_read_b128 v[200:203], v223 offset:36864
	ds_read_b128 v[204:207], v223 offset:37888
	ds_read_b128 v[224:227], v223 offset:38912
	ds_read_b128 v[228:231], v223 offset:39936
	s_add_i32 s13, s13, 0x80000
	s_mov_b32 m0, s82
	s_nop 0
	buffer_load_dwordx4 v220, s[64:67], s13 offen lds
	s_nop 0
	s_mov_b32 m0, s83
	s_nop 0
	buffer_load_dwordx4 v221, s[64:67], s13 offen lds
	s_waitcnt vmcnt(8) lgkmcnt(0)
	s_barrier
	s_waitcnt lgkmcnt(7)
	v_mfma_f32_16x16x32_bf16 v[164:167], v[128:131], v[184:187], v[164:167]
	v_mfma_f32_16x16x32_bf16 v[160:163], v[152:155], v[184:187], v[160:163]
	s_waitcnt lgkmcnt(5)
	v_mfma_f32_16x16x32_bf16 v[136:139], v[128:131], v[192:195], v[136:139]
	v_mfma_f32_16x16x32_bf16 v[132:135], v[152:155], v[192:195], v[132:135]
	s_waitcnt lgkmcnt(3)
	v_mfma_f32_16x16x32_bf16 v[116:119], v[128:131], v[200:203], v[116:119]
	v_mfma_f32_16x16x32_bf16 v[112:115], v[152:155], v[200:203], v[112:115]
	s_waitcnt lgkmcnt(1)
	v_mfma_f32_16x16x32_bf16 v[76:79], v[128:131], v[224:227], v[76:79]
	v_mfma_f32_16x16x32_bf16 v[72:75], v[152:155], v[224:227], v[72:75]
	v_mfma_f32_16x16x32_bf16 v[164:167], v[140:143], v[188:191], v[164:167]
	v_mfma_f32_16x16x32_bf16 v[160:163], v[156:159], v[188:191], v[160:163]
	v_mfma_f32_16x16x32_bf16 v[136:139], v[140:143], v[196:199], v[136:139]
	v_mfma_f32_16x16x32_bf16 v[132:135], v[156:159], v[196:199], v[132:135]
	v_mfma_f32_16x16x32_bf16 v[116:119], v[140:143], v[204:207], v[116:119]
	v_mfma_f32_16x16x32_bf16 v[112:115], v[156:159], v[204:207], v[112:115]
	s_waitcnt lgkmcnt(0)
	v_mfma_f32_16x16x32_bf16 v[76:79], v[140:143], v[228:231], v[76:79]
	v_mfma_f32_16x16x32_bf16 v[72:75], v[156:159], v[228:231], v[72:75]
	v_mfma_f32_16x16x32_bf16 v[148:151], v[168:171], v[184:187], v[148:151]
	v_mfma_f32_16x16x32_bf16 v[144:147], v[176:179], v[184:187], v[144:147]
	v_mfma_f32_16x16x32_bf16 v[124:127], v[168:171], v[192:195], v[124:127]
	v_mfma_f32_16x16x32_bf16 v[120:123], v[176:179], v[192:195], v[120:123]
	v_mfma_f32_16x16x32_bf16 v[108:111], v[168:171], v[200:203], v[108:111]
	v_mfma_f32_16x16x32_bf16 v[104:107], v[176:179], v[200:203], v[104:107]
	v_mfma_f32_16x16x32_bf16 v[68:71], v[168:171], v[224:227], v[68:71]
	v_mfma_f32_16x16x32_bf16 v[64:67], v[176:179], v[224:227], v[64:67]
	v_mfma_f32_16x16x32_bf16 v[148:151], v[172:175], v[188:191], v[148:151]
	v_mfma_f32_16x16x32_bf16 v[144:147], v[180:183], v[188:191], v[144:147]
	v_mfma_f32_16x16x32_bf16 v[124:127], v[172:175], v[196:199], v[124:127]
	v_mfma_f32_16x16x32_bf16 v[120:123], v[180:183], v[196:199], v[120:123]
	v_mfma_f32_16x16x32_bf16 v[108:111], v[172:175], v[204:207], v[108:111]
	v_mfma_f32_16x16x32_bf16 v[104:107], v[180:183], v[204:207], v[104:107]
	v_mfma_f32_16x16x32_bf16 v[68:71], v[172:175], v[228:231], v[68:71]
	v_mfma_f32_16x16x32_bf16 v[64:67], v[180:183], v[228:231], v[64:67]
	s_barrier
	ds_read_b128 v[184:187], v223 offset:49152
	ds_read_b128 v[188:191], v223 offset:50176
	ds_read_b128 v[192:195], v223 offset:51200
	ds_read_b128 v[196:199], v223 offset:52224
	ds_read_b128 v[200:203], v223 offset:53248
	ds_read_b128 v[204:207], v223 offset:54272
	ds_read_b128 v[224:227], v223 offset:55296
	ds_read_b128 v[228:231], v223 offset:56320
	s_or_b32 s13, s12, 0x4000
	s_mov_b32 m0, s34
	s_nop 0
	buffer_load_dwordx4 v220, s[48:51], s13 offen lds
	s_add_i32 s12, s12, 0x84000
	s_mov_b32 m0, s84
	s_nop 0
	buffer_load_dwordx4 v221, s[48:51], s13 offen lds
	s_nop 0
	s_mov_b32 m0, s87
	s_nop 0
	buffer_load_dwordx4 v220, s[48:51], s12 offen lds
	s_nop 0
	s_mov_b32 m0, s88
	s_nop 0
	buffer_load_dwordx4 v221, s[48:51], s12 offen lds
	s_nop 0
	s_mov_b32 m0, s85
	s_nop 0
	buffer_load_dwordx4 v220, s[64:67], s11 offen lds
	s_nop 0
	s_mov_b32 m0, s86
	s_nop 0
	buffer_load_dwordx4 v221, s[64:67], s11 offen lds
	s_waitcnt vmcnt(8) lgkmcnt(0)
	s_barrier
	s_waitcnt lgkmcnt(7)
	v_mfma_f32_16x16x32_bf16 v[60:63], v[128:131], v[184:187], v[60:63]
	v_mfma_f32_16x16x32_bf16 v[56:59], v[152:155], v[184:187], v[56:59]
	s_waitcnt lgkmcnt(5)
	v_mfma_f32_16x16x32_bf16 v[44:47], v[128:131], v[192:195], v[44:47]
	v_mfma_f32_16x16x32_bf16 v[40:43], v[152:155], v[192:195], v[40:43]
	s_waitcnt lgkmcnt(3)
	v_mfma_f32_16x16x32_bf16 v[28:31], v[128:131], v[200:203], v[28:31]
	v_mfma_f32_16x16x32_bf16 v[24:27], v[152:155], v[200:203], v[24:27]
	s_waitcnt lgkmcnt(1)
	v_mfma_f32_16x16x32_bf16 v[12:15], v[128:131], v[224:227], v[12:15]
	v_mfma_f32_16x16x32_bf16 v[8:11], v[152:155], v[224:227], v[8:11]
	v_mfma_f32_16x16x32_bf16 v[60:63], v[140:143], v[188:191], v[60:63]
	v_mfma_f32_16x16x32_bf16 v[56:59], v[156:159], v[188:191], v[56:59]
	v_mfma_f32_16x16x32_bf16 v[44:47], v[140:143], v[196:199], v[44:47]
	v_mfma_f32_16x16x32_bf16 v[40:43], v[156:159], v[196:199], v[40:43]
	v_mfma_f32_16x16x32_bf16 v[28:31], v[140:143], v[204:207], v[28:31]
	v_mfma_f32_16x16x32_bf16 v[24:27], v[156:159], v[204:207], v[24:27]
	s_waitcnt lgkmcnt(0)
	v_mfma_f32_16x16x32_bf16 v[12:15], v[140:143], v[228:231], v[12:15]
	v_mfma_f32_16x16x32_bf16 v[8:11], v[156:159], v[228:231], v[8:11]
	v_mfma_f32_16x16x32_bf16 v[52:55], v[168:171], v[184:187], v[52:55]
	v_mfma_f32_16x16x32_bf16 v[48:51], v[176:179], v[184:187], v[48:51]
	v_mfma_f32_16x16x32_bf16 v[36:39], v[168:171], v[192:195], v[36:39]
	v_mfma_f32_16x16x32_bf16 v[32:35], v[176:179], v[192:195], v[32:35]
	v_mfma_f32_16x16x32_bf16 v[20:23], v[168:171], v[200:203], v[20:23]
	v_mfma_f32_16x16x32_bf16 v[16:19], v[176:179], v[200:203], v[16:19]
	v_mfma_f32_16x16x32_bf16 v[4:7], v[168:171], v[224:227], v[4:7]
	v_mfma_f32_16x16x32_bf16 v[0:3], v[176:179], v[224:227], v[0:3]
	v_mfma_f32_16x16x32_bf16 v[52:55], v[172:175], v[188:191], v[52:55]
	v_mfma_f32_16x16x32_bf16 v[48:51], v[180:183], v[188:191], v[48:51]
	v_mfma_f32_16x16x32_bf16 v[36:39], v[172:175], v[196:199], v[36:39]
	v_mfma_f32_16x16x32_bf16 v[32:35], v[180:183], v[196:199], v[32:35]
	v_mfma_f32_16x16x32_bf16 v[20:23], v[172:175], v[204:207], v[20:23]
	v_mfma_f32_16x16x32_bf16 v[16:19], v[180:183], v[204:207], v[16:19]
	v_mfma_f32_16x16x32_bf16 v[4:7], v[172:175], v[228:231], v[4:7]
	v_mfma_f32_16x16x32_bf16 v[0:3], v[180:183], v[228:231], v[0:3]
	s_barrier
	s_add_i32 s10, s10, 2
	s_add_i32 s8, s8, 0x8000
	s_add_i32 s9, s9, 0x8000
.LBB0_691:
	v_add_u32_e32 v156, 0x10000, v222
	v_add_u32_e32 v180, 0x14000, v222
	ds_read_b128 v[128:131], v156
	ds_read_b128 v[140:143], v156 offset:1024
	ds_read_b128 v[152:155], v156 offset:2048
	ds_read_b128 v[156:159], v156 offset:3072
	ds_read_b128 v[168:171], v180
	ds_read_b128 v[172:175], v180 offset:1024
	ds_read_b128 v[176:179], v180 offset:2048
	ds_read_b128 v[180:183], v180 offset:3072
	s_add_i32 s11, s8, 0xfff84000
	s_cmp_eq_u32 s10, 28
	s_cselect_b32 s13, s6, s11
	s_cselect_b32 s12, s7, s9
	s_or_b32 s11, s13, 0x4000
	ds_read_b128 v[184:187], v223
	ds_read_b128 v[188:191], v223 offset:1024
	ds_read_b128 v[192:195], v223 offset:2048
	ds_read_b128 v[196:199], v223 offset:3072
	ds_read_b128 v[200:203], v223 offset:4096
	ds_read_b128 v[204:207], v223 offset:5120
	ds_read_b128 v[224:227], v223 offset:6144
	ds_read_b128 v[228:231], v223 offset:7168
	s_mov_b32 m0, s89
	s_nop 0
	buffer_load_dwordx4 v220, s[64:67], s8 offen lds
	s_nop 0
	s_mov_b32 m0, s91
	s_nop 0
	buffer_load_dwordx4 v221, s[64:67], s8 offen lds
	s_waitcnt vmcnt(8) lgkmcnt(0)
	s_barrier
	s_waitcnt lgkmcnt(7)
	v_mfma_f32_16x16x32_bf16 v[164:167], v[128:131], v[184:187], v[164:167]
	v_mfma_f32_16x16x32_bf16 v[160:163], v[152:155], v[184:187], v[160:163]
	s_waitcnt lgkmcnt(5)
	v_mfma_f32_16x16x32_bf16 v[136:139], v[128:131], v[192:195], v[136:139]
	v_mfma_f32_16x16x32_bf16 v[132:135], v[152:155], v[192:195], v[132:135]
	s_waitcnt lgkmcnt(3)
	v_mfma_f32_16x16x32_bf16 v[116:119], v[128:131], v[200:203], v[116:119]
	v_mfma_f32_16x16x32_bf16 v[112:115], v[152:155], v[200:203], v[112:115]
	s_waitcnt lgkmcnt(1)
	v_mfma_f32_16x16x32_bf16 v[76:79], v[128:131], v[224:227], v[76:79]
	v_mfma_f32_16x16x32_bf16 v[72:75], v[152:155], v[224:227], v[72:75]
	v_mfma_f32_16x16x32_bf16 v[164:167], v[140:143], v[188:191], v[164:167]
	v_mfma_f32_16x16x32_bf16 v[160:163], v[156:159], v[188:191], v[160:163]
	v_mfma_f32_16x16x32_bf16 v[136:139], v[140:143], v[196:199], v[136:139]
	v_mfma_f32_16x16x32_bf16 v[132:135], v[156:159], v[196:199], v[132:135]
	v_mfma_f32_16x16x32_bf16 v[116:119], v[140:143], v[204:207], v[116:119]
	v_mfma_f32_16x16x32_bf16 v[112:115], v[156:159], v[204:207], v[112:115]
	s_waitcnt lgkmcnt(0)
	v_mfma_f32_16x16x32_bf16 v[76:79], v[140:143], v[228:231], v[76:79]
	v_mfma_f32_16x16x32_bf16 v[72:75], v[156:159], v[228:231], v[72:75]
	v_mfma_f32_16x16x32_bf16 v[148:151], v[168:171], v[184:187], v[148:151]
	v_mfma_f32_16x16x32_bf16 v[144:147], v[176:179], v[184:187], v[144:147]
	v_mfma_f32_16x16x32_bf16 v[124:127], v[168:171], v[192:195], v[124:127]
	v_mfma_f32_16x16x32_bf16 v[120:123], v[176:179], v[192:195], v[120:123]
	v_mfma_f32_16x16x32_bf16 v[108:111], v[168:171], v[200:203], v[108:111]
	v_mfma_f32_16x16x32_bf16 v[104:107], v[176:179], v[200:203], v[104:107]
	v_mfma_f32_16x16x32_bf16 v[68:71], v[168:171], v[224:227], v[68:71]
	v_mfma_f32_16x16x32_bf16 v[64:67], v[176:179], v[224:227], v[64:67]
	v_mfma_f32_16x16x32_bf16 v[148:151], v[172:175], v[188:191], v[148:151]
	v_mfma_f32_16x16x32_bf16 v[144:147], v[180:183], v[188:191], v[144:147]
	v_mfma_f32_16x16x32_bf16 v[124:127], v[172:175], v[196:199], v[124:127]
	v_mfma_f32_16x16x32_bf16 v[120:123], v[180:183], v[196:199], v[120:123]
	v_mfma_f32_16x16x32_bf16 v[108:111], v[172:175], v[204:207], v[108:111]
	v_mfma_f32_16x16x32_bf16 v[104:107], v[180:183], v[204:207], v[104:107]
	v_mfma_f32_16x16x32_bf16 v[68:71], v[172:175], v[228:231], v[68:71]
	v_mfma_f32_16x16x32_bf16 v[64:67], v[180:183], v[228:231], v[64:67]
	s_barrier
	ds_read_b128 v[184:187], v223 offset:16384
	ds_read_b128 v[188:191], v223 offset:17408
	ds_read_b128 v[192:195], v223 offset:18432
	ds_read_b128 v[196:199], v223 offset:19456
	ds_read_b128 v[200:203], v223 offset:20480
	ds_read_b128 v[204:207], v223 offset:21504
	ds_read_b128 v[224:227], v223 offset:22528
	ds_read_b128 v[228:231], v223 offset:23552
	s_mov_b32 m0, s55
	s_nop 0
	buffer_load_dwordx4 v220, s[48:51], s12 offen lds
	s_add_i32 s14, s12, 0x80000
	s_mov_b32 m0, s76
	s_nop 0
	buffer_load_dwordx4 v221, s[48:51], s12 offen lds
	s_nop 0
	s_mov_b32 m0, s77
	s_nop 0
	buffer_load_dwordx4 v220, s[48:51], s14 offen lds
	s_nop 0
	s_mov_b32 m0, s78
	s_nop 0
	buffer_load_dwordx4 v221, s[48:51], s14 offen lds
	s_nop 0
	s_mov_b32 m0, s31
	s_nop 0
	buffer_load_dwordx4 v220, s[64:67], s13 offen lds
	s_nop 0
	s_mov_b32 m0, s79
	s_nop 0
	buffer_load_dwordx4 v221, s[64:67], s13 offen lds
	s_waitcnt vmcnt(8) lgkmcnt(0)
	s_barrier
	s_waitcnt lgkmcnt(7)
	v_mfma_f32_16x16x32_bf16 v[60:63], v[128:131], v[184:187], v[60:63]
	v_mfma_f32_16x16x32_bf16 v[56:59], v[152:155], v[184:187], v[56:59]
	s_waitcnt lgkmcnt(5)
	v_mfma_f32_16x16x32_bf16 v[44:47], v[128:131], v[192:195], v[44:47]
	v_mfma_f32_16x16x32_bf16 v[40:43], v[152:155], v[192:195], v[40:43]
	s_waitcnt lgkmcnt(3)
	v_mfma_f32_16x16x32_bf16 v[28:31], v[128:131], v[200:203], v[28:31]
	v_mfma_f32_16x16x32_bf16 v[24:27], v[152:155], v[200:203], v[24:27]
	s_waitcnt lgkmcnt(1)
	v_mfma_f32_16x16x32_bf16 v[12:15], v[128:131], v[224:227], v[12:15]
	v_mfma_f32_16x16x32_bf16 v[8:11], v[152:155], v[224:227], v[8:11]
	v_mfma_f32_16x16x32_bf16 v[60:63], v[140:143], v[188:191], v[60:63]
	v_mfma_f32_16x16x32_bf16 v[56:59], v[156:159], v[188:191], v[56:59]
	v_mfma_f32_16x16x32_bf16 v[44:47], v[140:143], v[196:199], v[44:47]
	v_mfma_f32_16x16x32_bf16 v[40:43], v[156:159], v[196:199], v[40:43]
	v_mfma_f32_16x16x32_bf16 v[28:31], v[140:143], v[204:207], v[28:31]
	v_mfma_f32_16x16x32_bf16 v[24:27], v[156:159], v[204:207], v[24:27]
	s_waitcnt lgkmcnt(0)
	v_mfma_f32_16x16x32_bf16 v[12:15], v[140:143], v[228:231], v[12:15]
	v_mfma_f32_16x16x32_bf16 v[8:11], v[156:159], v[228:231], v[8:11]
	v_mfma_f32_16x16x32_bf16 v[52:55], v[168:171], v[184:187], v[52:55]
	v_mfma_f32_16x16x32_bf16 v[48:51], v[176:179], v[184:187], v[48:51]
	v_mfma_f32_16x16x32_bf16 v[36:39], v[168:171], v[192:195], v[36:39]
	v_mfma_f32_16x16x32_bf16 v[32:35], v[176:179], v[192:195], v[32:35]
	v_mfma_f32_16x16x32_bf16 v[20:23], v[168:171], v[200:203], v[20:23]
	v_mfma_f32_16x16x32_bf16 v[16:19], v[176:179], v[200:203], v[16:19]
	v_mfma_f32_16x16x32_bf16 v[4:7], v[168:171], v[224:227], v[4:7]
	v_mfma_f32_16x16x32_bf16 v[0:3], v[176:179], v[224:227], v[0:3]
	v_mfma_f32_16x16x32_bf16 v[52:55], v[172:175], v[188:191], v[52:55]
	v_mfma_f32_16x16x32_bf16 v[48:51], v[180:183], v[188:191], v[48:51]
	v_mfma_f32_16x16x32_bf16 v[36:39], v[172:175], v[196:199], v[36:39]
	v_mfma_f32_16x16x32_bf16 v[32:35], v[180:183], v[196:199], v[32:35]
	v_mfma_f32_16x16x32_bf16 v[20:23], v[172:175], v[204:207], v[20:23]
	v_mfma_f32_16x16x32_bf16 v[16:19], v[180:183], v[204:207], v[16:19]
	v_mfma_f32_16x16x32_bf16 v[4:7], v[172:175], v[228:231], v[4:7]
	v_mfma_f32_16x16x32_bf16 v[0:3], v[180:183], v[228:231], v[0:3]
	s_barrier
	v_add_u32_e32 v156, 0x18000, v222
	v_add_u32_e32 v180, 0x1c000, v222
	ds_read_b128 v[128:131], v156
	ds_read_b128 v[140:143], v156 offset:1024
	ds_read_b128 v[152:155], v156 offset:2048
	ds_read_b128 v[156:159], v156 offset:3072
	ds_read_b128 v[168:171], v180
	ds_read_b128 v[172:175], v180 offset:1024
	ds_read_b128 v[176:179], v180 offset:2048
	ds_read_b128 v[180:183], v180 offset:3072
	ds_read_b128 v[184:187], v223 offset:32768
	ds_read_b128 v[188:191], v223 offset:33792
	ds_read_b128 v[192:195], v223 offset:34816
	ds_read_b128 v[196:199], v223 offset:35840
	ds_read_b128 v[200:203], v223 offset:36864
	ds_read_b128 v[204:207], v223 offset:37888
	ds_read_b128 v[224:227], v223 offset:38912
	ds_read_b128 v[228:231], v223 offset:39936
	s_add_i32 s13, s13, 0x80000
	s_mov_b32 m0, s82
	s_nop 0
	buffer_load_dwordx4 v220, s[64:67], s13 offen lds
	s_nop 0
	s_mov_b32 m0, s83
	s_nop 0
	buffer_load_dwordx4 v221, s[64:67], s13 offen lds
	s_waitcnt vmcnt(8) lgkmcnt(0)
	s_barrier
	s_waitcnt lgkmcnt(7)
	v_mfma_f32_16x16x32_bf16 v[164:167], v[128:131], v[184:187], v[164:167]
	v_mfma_f32_16x16x32_bf16 v[160:163], v[152:155], v[184:187], v[160:163]
	s_waitcnt lgkmcnt(5)
	v_mfma_f32_16x16x32_bf16 v[136:139], v[128:131], v[192:195], v[136:139]
	v_mfma_f32_16x16x32_bf16 v[132:135], v[152:155], v[192:195], v[132:135]
	s_waitcnt lgkmcnt(3)
	v_mfma_f32_16x16x32_bf16 v[116:119], v[128:131], v[200:203], v[116:119]
	v_mfma_f32_16x16x32_bf16 v[112:115], v[152:155], v[200:203], v[112:115]
	s_waitcnt lgkmcnt(1)
	v_mfma_f32_16x16x32_bf16 v[76:79], v[128:131], v[224:227], v[76:79]
	v_mfma_f32_16x16x32_bf16 v[72:75], v[152:155], v[224:227], v[72:75]
	v_mfma_f32_16x16x32_bf16 v[164:167], v[140:143], v[188:191], v[164:167]
	v_mfma_f32_16x16x32_bf16 v[160:163], v[156:159], v[188:191], v[160:163]
	v_mfma_f32_16x16x32_bf16 v[136:139], v[140:143], v[196:199], v[136:139]
	v_mfma_f32_16x16x32_bf16 v[132:135], v[156:159], v[196:199], v[132:135]
	v_mfma_f32_16x16x32_bf16 v[116:119], v[140:143], v[204:207], v[116:119]
	v_mfma_f32_16x16x32_bf16 v[112:115], v[156:159], v[204:207], v[112:115]
	s_waitcnt lgkmcnt(0)
	v_mfma_f32_16x16x32_bf16 v[76:79], v[140:143], v[228:231], v[76:79]
	v_mfma_f32_16x16x32_bf16 v[72:75], v[156:159], v[228:231], v[72:75]
	v_mfma_f32_16x16x32_bf16 v[148:151], v[168:171], v[184:187], v[148:151]
	v_mfma_f32_16x16x32_bf16 v[144:147], v[176:179], v[184:187], v[144:147]
	v_mfma_f32_16x16x32_bf16 v[124:127], v[168:171], v[192:195], v[124:127]
	v_mfma_f32_16x16x32_bf16 v[120:123], v[176:179], v[192:195], v[120:123]
	v_mfma_f32_16x16x32_bf16 v[108:111], v[168:171], v[200:203], v[108:111]
	v_mfma_f32_16x16x32_bf16 v[104:107], v[176:179], v[200:203], v[104:107]
	v_mfma_f32_16x16x32_bf16 v[68:71], v[168:171], v[224:227], v[68:71]
	v_mfma_f32_16x16x32_bf16 v[64:67], v[176:179], v[224:227], v[64:67]
	v_mfma_f32_16x16x32_bf16 v[148:151], v[172:175], v[188:191], v[148:151]
	v_mfma_f32_16x16x32_bf16 v[144:147], v[180:183], v[188:191], v[144:147]
	v_mfma_f32_16x16x32_bf16 v[124:127], v[172:175], v[196:199], v[124:127]
	v_mfma_f32_16x16x32_bf16 v[120:123], v[180:183], v[196:199], v[120:123]
	v_mfma_f32_16x16x32_bf16 v[108:111], v[172:175], v[204:207], v[108:111]
	v_mfma_f32_16x16x32_bf16 v[104:107], v[180:183], v[204:207], v[104:107]
	v_mfma_f32_16x16x32_bf16 v[68:71], v[172:175], v[228:231], v[68:71]
	v_mfma_f32_16x16x32_bf16 v[64:67], v[180:183], v[228:231], v[64:67]
	s_barrier
	ds_read_b128 v[184:187], v223 offset:49152
	ds_read_b128 v[188:191], v223 offset:50176
	ds_read_b128 v[192:195], v223 offset:51200
	ds_read_b128 v[196:199], v223 offset:52224
	ds_read_b128 v[200:203], v223 offset:53248
	ds_read_b128 v[204:207], v223 offset:54272
	ds_read_b128 v[224:227], v223 offset:55296
	ds_read_b128 v[228:231], v223 offset:56320
	s_or_b32 s13, s12, 0x4000
	s_mov_b32 m0, s34
	s_nop 0
	buffer_load_dwordx4 v220, s[48:51], s13 offen lds
	s_add_i32 s12, s12, 0x84000
	s_mov_b32 m0, s84
	s_nop 0
	buffer_load_dwordx4 v221, s[48:51], s13 offen lds
	s_nop 0
	s_mov_b32 m0, s87
	s_nop 0
	buffer_load_dwordx4 v220, s[48:51], s12 offen lds
	s_nop 0
	s_mov_b32 m0, s88
	s_nop 0
	buffer_load_dwordx4 v221, s[48:51], s12 offen lds
	s_nop 0
	s_mov_b32 m0, s85
	s_nop 0
	buffer_load_dwordx4 v220, s[64:67], s11 offen lds
	s_nop 0
	s_mov_b32 m0, s86
	s_nop 0
	buffer_load_dwordx4 v221, s[64:67], s11 offen lds
	s_waitcnt vmcnt(8) lgkmcnt(0)
	s_barrier
	s_waitcnt lgkmcnt(7)
	v_mfma_f32_16x16x32_bf16 v[60:63], v[128:131], v[184:187], v[60:63]
	v_mfma_f32_16x16x32_bf16 v[56:59], v[152:155], v[184:187], v[56:59]
	s_waitcnt lgkmcnt(5)
	v_mfma_f32_16x16x32_bf16 v[44:47], v[128:131], v[192:195], v[44:47]
	v_mfma_f32_16x16x32_bf16 v[40:43], v[152:155], v[192:195], v[40:43]
	s_waitcnt lgkmcnt(3)
	v_mfma_f32_16x16x32_bf16 v[28:31], v[128:131], v[200:203], v[28:31]
	v_mfma_f32_16x16x32_bf16 v[24:27], v[152:155], v[200:203], v[24:27]
	s_waitcnt lgkmcnt(1)
	v_mfma_f32_16x16x32_bf16 v[12:15], v[128:131], v[224:227], v[12:15]
	v_mfma_f32_16x16x32_bf16 v[8:11], v[152:155], v[224:227], v[8:11]
	v_mfma_f32_16x16x32_bf16 v[60:63], v[140:143], v[188:191], v[60:63]
	v_mfma_f32_16x16x32_bf16 v[56:59], v[156:159], v[188:191], v[56:59]
	v_mfma_f32_16x16x32_bf16 v[44:47], v[140:143], v[196:199], v[44:47]
	v_mfma_f32_16x16x32_bf16 v[40:43], v[156:159], v[196:199], v[40:43]
	v_mfma_f32_16x16x32_bf16 v[28:31], v[140:143], v[204:207], v[28:31]
	v_mfma_f32_16x16x32_bf16 v[24:27], v[156:159], v[204:207], v[24:27]
	s_waitcnt lgkmcnt(0)
	v_mfma_f32_16x16x32_bf16 v[12:15], v[140:143], v[228:231], v[12:15]
	v_mfma_f32_16x16x32_bf16 v[8:11], v[156:159], v[228:231], v[8:11]
	v_mfma_f32_16x16x32_bf16 v[52:55], v[168:171], v[184:187], v[52:55]
	v_mfma_f32_16x16x32_bf16 v[48:51], v[176:179], v[184:187], v[48:51]
	v_mfma_f32_16x16x32_bf16 v[36:39], v[168:171], v[192:195], v[36:39]
	v_mfma_f32_16x16x32_bf16 v[32:35], v[176:179], v[192:195], v[32:35]
	v_mfma_f32_16x16x32_bf16 v[20:23], v[168:171], v[200:203], v[20:23]
	v_mfma_f32_16x16x32_bf16 v[16:19], v[176:179], v[200:203], v[16:19]
	v_mfma_f32_16x16x32_bf16 v[4:7], v[168:171], v[224:227], v[4:7]
	v_mfma_f32_16x16x32_bf16 v[0:3], v[176:179], v[224:227], v[0:3]
	v_mfma_f32_16x16x32_bf16 v[52:55], v[172:175], v[188:191], v[52:55]
	v_mfma_f32_16x16x32_bf16 v[48:51], v[180:183], v[188:191], v[48:51]
	v_mfma_f32_16x16x32_bf16 v[36:39], v[172:175], v[196:199], v[36:39]
	v_mfma_f32_16x16x32_bf16 v[32:35], v[180:183], v[196:199], v[32:35]
	v_mfma_f32_16x16x32_bf16 v[20:23], v[172:175], v[204:207], v[20:23]
	v_mfma_f32_16x16x32_bf16 v[16:19], v[180:183], v[204:207], v[16:19]
	v_mfma_f32_16x16x32_bf16 v[4:7], v[172:175], v[228:231], v[4:7]
	v_mfma_f32_16x16x32_bf16 v[0:3], v[180:183], v[228:231], v[0:3]
	s_barrier
	s_add_i32 s10, s10, 2
	s_add_i32 s8, s8, 0x8000
	s_add_i32 s9, s9, 0x8000
	s_cmp_gt_u32 s10, 29
	s_cbranch_scc0 .LBB0_691

.Lnb_p5:
	s_add_i32 s53, s37, 0xfff84000
	s_cmp_eq_u32 s52, 28
	s_cselect_b32 s56, s4, s53
	s_cselect_b32 s55, s5, s51
	s_or_b32 s53, s56, 0x4000
	s_mov_b32 m0, s41
	s_nop 0
	buffer_load_dwordx4 v166, s[24:27], s37 offen lds
	s_nop 0
	s_mov_b32 m0, s42
	s_nop 0
	buffer_load_dwordx4 v167, s[24:27], s37 offen lds
	s_waitcnt vmcnt(24) lgkmcnt(0)
	s_barrier
	s_waitcnt lgkmcnt(7)
	v_mfma_f32_16x16x32_bf16 v[148:151], v[152:155], v[190:193], 0
	v_mfma_f32_16x16x32_bf16 v[140:143], v[160:163], v[190:193], 0
	s_waitcnt lgkmcnt(5)
	v_mfma_f32_16x16x32_bf16 v[132:135], v[152:155], v[198:201], 0
	v_mfma_f32_16x16x32_bf16 v[124:127], v[160:163], v[198:201], 0
	s_waitcnt lgkmcnt(3)
	v_mfma_f32_16x16x32_bf16 v[116:119], v[152:155], v[220:223], 0
	v_mfma_f32_16x16x32_bf16 v[108:111], v[160:163], v[220:223], 0
	s_waitcnt lgkmcnt(1)
	v_mfma_f32_16x16x32_bf16 v[76:79], v[152:155], v[228:231], 0
	v_mfma_f32_16x16x32_bf16 v[68:71], v[160:163], v[228:231], 0
	v_mfma_f32_16x16x32_bf16 v[148:151], v[156:159], v[194:197], v[148:151]
	v_mfma_f32_16x16x32_bf16 v[140:143], v[170:173], v[194:197], v[140:143]
	v_mfma_f32_16x16x32_bf16 v[132:135], v[156:159], v[202:205], v[132:135]
	v_mfma_f32_16x16x32_bf16 v[124:127], v[170:173], v[202:205], v[124:127]
	v_mfma_f32_16x16x32_bf16 v[116:119], v[156:159], v[224:227], v[116:119]
	v_mfma_f32_16x16x32_bf16 v[108:111], v[170:173], v[224:227], v[108:111]
	s_waitcnt lgkmcnt(0)
	v_mfma_f32_16x16x32_bf16 v[76:79], v[156:159], v[240:243], v[76:79]
	v_mfma_f32_16x16x32_bf16 v[68:71], v[170:173], v[240:243], v[68:71]
	v_mfma_f32_16x16x32_bf16 v[144:147], v[174:177], v[190:193], 0
	v_mfma_f32_16x16x32_bf16 v[136:139], v[182:185], v[190:193], 0
	v_mfma_f32_16x16x32_bf16 v[128:131], v[174:177], v[198:201], 0
	v_mfma_f32_16x16x32_bf16 v[120:123], v[182:185], v[198:201], 0
	v_mfma_f32_16x16x32_bf16 v[112:115], v[174:177], v[220:223], 0
	v_mfma_f32_16x16x32_bf16 v[104:107], v[182:185], v[220:223], 0
	v_mfma_f32_16x16x32_bf16 v[72:75], v[174:177], v[228:231], 0
	v_mfma_f32_16x16x32_bf16 v[64:67], v[182:185], v[228:231], 0
	v_mfma_f32_16x16x32_bf16 v[144:147], v[178:181], v[194:197], v[144:147]
	v_mfma_f32_16x16x32_bf16 v[136:139], v[186:189], v[194:197], v[136:139]
	v_mfma_f32_16x16x32_bf16 v[128:131], v[178:181], v[202:205], v[128:131]
	v_mfma_f32_16x16x32_bf16 v[120:123], v[186:189], v[202:205], v[120:123]
	v_mfma_f32_16x16x32_bf16 v[112:115], v[178:181], v[224:227], v[112:115]
	v_mfma_f32_16x16x32_bf16 v[104:107], v[186:189], v[224:227], v[104:107]
	v_mfma_f32_16x16x32_bf16 v[72:75], v[178:181], v[240:243], v[72:75]
	v_mfma_f32_16x16x32_bf16 v[64:67], v[186:189], v[240:243], v[64:67]
	s_barrier
	ds_read_b128 v[190:193], v169 offset:16384
	ds_read_b128 v[194:197], v169 offset:17408
	ds_read_b128 v[198:201], v169 offset:18432
	ds_read_b128 v[202:205], v169 offset:19456
	ds_read_b128 v[220:223], v169 offset:20480
	ds_read_b128 v[224:227], v169 offset:21504
	ds_read_b128 v[228:231], v169 offset:22528
	ds_read_b128 v[240:243], v169 offset:23552
	s_mov_b32 m0, s7
	s_nop 0
	buffer_load_dwordx4 v166, s[28:31], s55 offen lds
	s_add_i32 s57, s55, 0x80000
	s_mov_b32 m0, s8
	s_nop 0
	buffer_load_dwordx4 v167, s[28:31], s55 offen lds
	s_nop 0
	s_mov_b32 m0, s9
	s_nop 0
	buffer_load_dwordx4 v166, s[28:31], s57 offen lds
	s_nop 0
	s_mov_b32 m0, s10
	s_nop 0
	buffer_load_dwordx4 v167, s[28:31], s57 offen lds
	s_nop 0
	s_mov_b32 m0, s6
	s_nop 0
	buffer_load_dwordx4 v166, s[24:27], s56 offen lds
	s_nop 0
	s_mov_b32 m0, s11
	s_nop 0
	buffer_load_dwordx4 v167, s[24:27], s56 offen lds
	s_waitcnt vmcnt(24) lgkmcnt(0)
	s_barrier
	s_waitcnt lgkmcnt(7)
	v_mfma_f32_16x16x32_bf16 v[60:63], v[152:155], v[190:193], 0
	v_mfma_f32_16x16x32_bf16 v[52:55], v[160:163], v[190:193], 0
	s_waitcnt lgkmcnt(5)
	v_mfma_f32_16x16x32_bf16 v[44:47], v[152:155], v[198:201], 0
	v_mfma_f32_16x16x32_bf16 v[36:39], v[160:163], v[198:201], 0
	s_waitcnt lgkmcnt(3)
	v_mfma_f32_16x16x32_bf16 v[28:31], v[152:155], v[220:223], 0
	v_mfma_f32_16x16x32_bf16 v[20:23], v[160:163], v[220:223], 0
	s_waitcnt lgkmcnt(1)
	v_mfma_f32_16x16x32_bf16 v[12:15], v[152:155], v[228:231], 0
	v_mfma_f32_16x16x32_bf16 v[4:7], v[160:163], v[228:231], 0
	v_mfma_f32_16x16x32_bf16 v[60:63], v[156:159], v[194:197], v[60:63]
	v_mfma_f32_16x16x32_bf16 v[52:55], v[170:173], v[194:197], v[52:55]
	v_mfma_f32_16x16x32_bf16 v[44:47], v[156:159], v[202:205], v[44:47]
	v_mfma_f32_16x16x32_bf16 v[36:39], v[170:173], v[202:205], v[36:39]
	v_mfma_f32_16x16x32_bf16 v[28:31], v[156:159], v[224:227], v[28:31]
	v_mfma_f32_16x16x32_bf16 v[20:23], v[170:173], v[224:227], v[20:23]
	s_waitcnt lgkmcnt(0)
	v_mfma_f32_16x16x32_bf16 v[12:15], v[156:159], v[240:243], v[12:15]
	v_mfma_f32_16x16x32_bf16 v[4:7], v[170:173], v[240:243], v[4:7]
	v_mfma_f32_16x16x32_bf16 v[56:59], v[174:177], v[190:193], 0
	v_mfma_f32_16x16x32_bf16 v[48:51], v[182:185], v[190:193], 0
	v_mfma_f32_16x16x32_bf16 v[40:43], v[174:177], v[198:201], 0
	v_mfma_f32_16x16x32_bf16 v[32:35], v[182:185], v[198:201], 0
	v_mfma_f32_16x16x32_bf16 v[24:27], v[174:177], v[220:223], 0
	v_mfma_f32_16x16x32_bf16 v[16:19], v[182:185], v[220:223], 0
	v_mfma_f32_16x16x32_bf16 v[8:11], v[174:177], v[228:231], 0
	v_mfma_f32_16x16x32_bf16 v[0:3], v[182:185], v[228:231], 0
	v_mfma_f32_16x16x32_bf16 v[56:59], v[178:181], v[194:197], v[56:59]
	v_mfma_f32_16x16x32_bf16 v[48:51], v[186:189], v[194:197], v[48:51]
	v_mfma_f32_16x16x32_bf16 v[40:43], v[178:181], v[202:205], v[40:43]
	v_mfma_f32_16x16x32_bf16 v[32:35], v[186:189], v[202:205], v[32:35]
	v_mfma_f32_16x16x32_bf16 v[24:27], v[178:181], v[224:227], v[24:27]
	v_mfma_f32_16x16x32_bf16 v[16:19], v[186:189], v[224:227], v[16:19]
	v_mfma_f32_16x16x32_bf16 v[8:11], v[178:181], v[240:243], v[8:11]
	v_mfma_f32_16x16x32_bf16 v[0:3], v[186:189], v[240:243], v[0:3]
	s_barrier
	v_add_u32_e32 v164, 0x18000, v168
	ds_read_b128 v[152:155], v164
	ds_read_b128 v[156:159], v164 offset:1024
	ds_read_b128 v[160:163], v164 offset:2048
	ds_read_b128 v[170:173], v164 offset:3072
	v_add_u32_e32 v164, 0x1c000, v168
	ds_read_b128 v[174:177], v164
	ds_read_b128 v[178:181], v164 offset:1024
	ds_read_b128 v[182:185], v164 offset:2048
	ds_read_b128 v[186:189], v164 offset:3072
	ds_read_b128 v[190:193], v169 offset:32768
	ds_read_b128 v[194:197], v169 offset:33792
	ds_read_b128 v[198:201], v169 offset:34816
	ds_read_b128 v[202:205], v169 offset:35840
	ds_read_b128 v[220:223], v169 offset:36864
	ds_read_b128 v[224:227], v169 offset:37888
	ds_read_b128 v[228:231], v169 offset:38912
	ds_read_b128 v[240:243], v169 offset:39936
	s_add_i32 s56, s56, 0x80000
	s_mov_b32 m0, s12
	s_nop 0
	buffer_load_dwordx4 v166, s[24:27], s56 offen lds
	s_nop 0
	s_mov_b32 m0, s13
	s_nop 0
	buffer_load_dwordx4 v167, s[24:27], s56 offen lds
	s_waitcnt vmcnt(8) lgkmcnt(0)
	s_barrier
	s_waitcnt lgkmcnt(7)
	v_mfma_f32_16x16x32_bf16 v[148:151], v[152:155], v[190:193], v[148:151]
	v_mfma_f32_16x16x32_bf16 v[140:143], v[160:163], v[190:193], v[140:143]
	s_waitcnt lgkmcnt(5)
	v_mfma_f32_16x16x32_bf16 v[132:135], v[152:155], v[198:201], v[132:135]
	v_mfma_f32_16x16x32_bf16 v[124:127], v[160:163], v[198:201], v[124:127]
	s_waitcnt lgkmcnt(3)
	v_mfma_f32_16x16x32_bf16 v[116:119], v[152:155], v[220:223], v[116:119]
	v_mfma_f32_16x16x32_bf16 v[108:111], v[160:163], v[220:223], v[108:111]
	s_waitcnt lgkmcnt(1)
	v_mfma_f32_16x16x32_bf16 v[76:79], v[152:155], v[228:231], v[76:79]
	v_mfma_f32_16x16x32_bf16 v[68:71], v[160:163], v[228:231], v[68:71]
	v_mfma_f32_16x16x32_bf16 v[148:151], v[156:159], v[194:197], v[148:151]
	v_mfma_f32_16x16x32_bf16 v[140:143], v[170:173], v[194:197], v[140:143]
	v_mfma_f32_16x16x32_bf16 v[132:135], v[156:159], v[202:205], v[132:135]
	v_mfma_f32_16x16x32_bf16 v[124:127], v[170:173], v[202:205], v[124:127]
	v_mfma_f32_16x16x32_bf16 v[116:119], v[156:159], v[224:227], v[116:119]
	v_mfma_f32_16x16x32_bf16 v[108:111], v[170:173], v[224:227], v[108:111]
	s_waitcnt lgkmcnt(0)
	v_mfma_f32_16x16x32_bf16 v[76:79], v[156:159], v[240:243], v[76:79]
	v_mfma_f32_16x16x32_bf16 v[68:71], v[170:173], v[240:243], v[68:71]
	v_mfma_f32_16x16x32_bf16 v[144:147], v[174:177], v[190:193], v[144:147]
	v_mfma_f32_16x16x32_bf16 v[136:139], v[182:185], v[190:193], v[136:139]
	v_mfma_f32_16x16x32_bf16 v[128:131], v[174:177], v[198:201], v[128:131]
	v_mfma_f32_16x16x32_bf16 v[120:123], v[182:185], v[198:201], v[120:123]
	v_mfma_f32_16x16x32_bf16 v[112:115], v[174:177], v[220:223], v[112:115]
	v_mfma_f32_16x16x32_bf16 v[104:107], v[182:185], v[220:223], v[104:107]
	v_mfma_f32_16x16x32_bf16 v[72:75], v[174:177], v[228:231], v[72:75]
	v_mfma_f32_16x16x32_bf16 v[64:67], v[182:185], v[228:231], v[64:67]
	v_mfma_f32_16x16x32_bf16 v[144:147], v[178:181], v[194:197], v[144:147]
	v_mfma_f32_16x16x32_bf16 v[136:139], v[186:189], v[194:197], v[136:139]
	v_mfma_f32_16x16x32_bf16 v[128:131], v[178:181], v[202:205], v[128:131]
	v_mfma_f32_16x16x32_bf16 v[120:123], v[186:189], v[202:205], v[120:123]
	v_mfma_f32_16x16x32_bf16 v[112:115], v[178:181], v[224:227], v[112:115]
	v_mfma_f32_16x16x32_bf16 v[104:107], v[186:189], v[224:227], v[104:107]
	v_mfma_f32_16x16x32_bf16 v[72:75], v[178:181], v[240:243], v[72:75]
	v_mfma_f32_16x16x32_bf16 v[64:67], v[186:189], v[240:243], v[64:67]
	s_barrier
	ds_read_b128 v[190:193], v169 offset:49152
	ds_read_b128 v[194:197], v169 offset:50176
	ds_read_b128 v[198:201], v169 offset:51200
	ds_read_b128 v[202:205], v169 offset:52224
	ds_read_b128 v[220:223], v169 offset:53248
	ds_read_b128 v[224:227], v169 offset:54272
	ds_read_b128 v[228:231], v169 offset:55296
	ds_read_b128 v[240:243], v169 offset:56320
	s_or_b32 s56, s55, 0x4000
	s_mov_b32 m0, s16
	s_nop 0
	buffer_load_dwordx4 v166, s[28:31], s56 offen lds
	s_add_i32 s55, s55, 0x84000
	s_mov_b32 m0, s17
	s_nop 0
	buffer_load_dwordx4 v167, s[28:31], s56 offen lds
	s_nop 0
	s_mov_b32 m0, s34
	s_nop 0
	buffer_load_dwordx4 v166, s[28:31], s55 offen lds
	s_nop 0
	s_mov_b32 m0, s40
	s_nop 0
	buffer_load_dwordx4 v167, s[28:31], s55 offen lds
	s_nop 0
	s_mov_b32 m0, s18
	s_nop 0
	buffer_load_dwordx4 v166, s[24:27], s53 offen lds
	s_nop 0
	s_mov_b32 m0, s19
	s_nop 0
	buffer_load_dwordx4 v167, s[24:27], s53 offen lds
	s_waitcnt vmcnt(8) lgkmcnt(0)
	s_barrier
	s_waitcnt lgkmcnt(7)
	v_mfma_f32_16x16x32_bf16 v[60:63], v[152:155], v[190:193], v[60:63]
	v_mfma_f32_16x16x32_bf16 v[52:55], v[160:163], v[190:193], v[52:55]
	s_waitcnt lgkmcnt(5)
	v_mfma_f32_16x16x32_bf16 v[44:47], v[152:155], v[198:201], v[44:47]
	v_mfma_f32_16x16x32_bf16 v[36:39], v[160:163], v[198:201], v[36:39]
	s_waitcnt lgkmcnt(3)
	v_mfma_f32_16x16x32_bf16 v[28:31], v[152:155], v[220:223], v[28:31]
	v_mfma_f32_16x16x32_bf16 v[20:23], v[160:163], v[220:223], v[20:23]
	s_waitcnt lgkmcnt(1)
	v_mfma_f32_16x16x32_bf16 v[12:15], v[152:155], v[228:231], v[12:15]
	v_mfma_f32_16x16x32_bf16 v[4:7], v[160:163], v[228:231], v[4:7]
	v_mfma_f32_16x16x32_bf16 v[60:63], v[156:159], v[194:197], v[60:63]
	v_mfma_f32_16x16x32_bf16 v[52:55], v[170:173], v[194:197], v[52:55]
	v_mfma_f32_16x16x32_bf16 v[44:47], v[156:159], v[202:205], v[44:47]
	v_mfma_f32_16x16x32_bf16 v[36:39], v[170:173], v[202:205], v[36:39]
	v_mfma_f32_16x16x32_bf16 v[28:31], v[156:159], v[224:227], v[28:31]
	v_mfma_f32_16x16x32_bf16 v[20:23], v[170:173], v[224:227], v[20:23]
	s_waitcnt lgkmcnt(0)
	v_mfma_f32_16x16x32_bf16 v[12:15], v[156:159], v[240:243], v[12:15]
	v_mfma_f32_16x16x32_bf16 v[4:7], v[170:173], v[240:243], v[4:7]
	v_mfma_f32_16x16x32_bf16 v[56:59], v[174:177], v[190:193], v[56:59]
	v_mfma_f32_16x16x32_bf16 v[48:51], v[182:185], v[190:193], v[48:51]
	v_mfma_f32_16x16x32_bf16 v[40:43], v[174:177], v[198:201], v[40:43]
	v_mfma_f32_16x16x32_bf16 v[32:35], v[182:185], v[198:201], v[32:35]
	v_mfma_f32_16x16x32_bf16 v[24:27], v[174:177], v[220:223], v[24:27]
	v_mfma_f32_16x16x32_bf16 v[16:19], v[182:185], v[220:223], v[16:19]
	v_mfma_f32_16x16x32_bf16 v[8:11], v[174:177], v[228:231], v[8:11]
	v_mfma_f32_16x16x32_bf16 v[0:3], v[182:185], v[228:231], v[0:3]
	v_mfma_f32_16x16x32_bf16 v[56:59], v[178:181], v[194:197], v[56:59]
	v_mfma_f32_16x16x32_bf16 v[48:51], v[186:189], v[194:197], v[48:51]
	v_mfma_f32_16x16x32_bf16 v[40:43], v[178:181], v[202:205], v[40:43]
	v_mfma_f32_16x16x32_bf16 v[32:35], v[186:189], v[202:205], v[32:35]
	v_mfma_f32_16x16x32_bf16 v[24:27], v[178:181], v[224:227], v[24:27]
	v_mfma_f32_16x16x32_bf16 v[16:19], v[186:189], v[224:227], v[16:19]
	v_mfma_f32_16x16x32_bf16 v[8:11], v[178:181], v[240:243], v[8:11]
	v_mfma_f32_16x16x32_bf16 v[0:3], v[186:189], v[240:243], v[0:3]
	s_barrier
	s_add_i32 s52, s52, 2
	s_add_i32 s37, s37, 0x8000
	s_add_i32 s51, s51, 0x8000
.LBB0_795:
	v_add_u32_e32 v164, 0x10000, v168
	ds_read_b128 v[152:155], v164
	ds_read_b128 v[156:159], v164 offset:1024
	ds_read_b128 v[160:163], v164 offset:2048
	ds_read_b128 v[170:173], v164 offset:3072
	v_add_u32_e32 v164, 0x14000, v168
	ds_read_b128 v[174:177], v164
	ds_read_b128 v[178:181], v164 offset:1024
	ds_read_b128 v[182:185], v164 offset:2048
	ds_read_b128 v[186:189], v164 offset:3072
	s_add_i32 s53, s37, 0xfff84000
	s_cmp_eq_u32 s52, 28
	s_cselect_b32 s56, s4, s53
	s_cselect_b32 s55, s5, s51
	s_or_b32 s53, s56, 0x4000
	ds_read_b128 v[190:193], v169
	ds_read_b128 v[194:197], v169 offset:1024
	ds_read_b128 v[198:201], v169 offset:2048
	ds_read_b128 v[202:205], v169 offset:3072
	ds_read_b128 v[220:223], v169 offset:4096
	ds_read_b128 v[224:227], v169 offset:5120
	ds_read_b128 v[228:231], v169 offset:6144
	ds_read_b128 v[240:243], v169 offset:7168
	s_mov_b32 m0, s41
	s_nop 0
	buffer_load_dwordx4 v166, s[24:27], s37 offen lds
	s_nop 0
	s_mov_b32 m0, s42
	s_nop 0
	buffer_load_dwordx4 v167, s[24:27], s37 offen lds
	s_waitcnt vmcnt(8) lgkmcnt(0)
	s_barrier
	s_waitcnt lgkmcnt(7)
	v_mfma_f32_16x16x32_bf16 v[148:151], v[152:155], v[190:193], v[148:151]
	v_mfma_f32_16x16x32_bf16 v[140:143], v[160:163], v[190:193], v[140:143]
	s_waitcnt lgkmcnt(5)
	v_mfma_f32_16x16x32_bf16 v[132:135], v[152:155], v[198:201], v[132:135]
	v_mfma_f32_16x16x32_bf16 v[124:127], v[160:163], v[198:201], v[124:127]
	s_waitcnt lgkmcnt(3)
	v_mfma_f32_16x16x32_bf16 v[116:119], v[152:155], v[220:223], v[116:119]
	v_mfma_f32_16x16x32_bf16 v[108:111], v[160:163], v[220:223], v[108:111]
	s_waitcnt lgkmcnt(1)
	v_mfma_f32_16x16x32_bf16 v[76:79], v[152:155], v[228:231], v[76:79]
	v_mfma_f32_16x16x32_bf16 v[68:71], v[160:163], v[228:231], v[68:71]
	v_mfma_f32_16x16x32_bf16 v[148:151], v[156:159], v[194:197], v[148:151]
	v_mfma_f32_16x16x32_bf16 v[140:143], v[170:173], v[194:197], v[140:143]
	v_mfma_f32_16x16x32_bf16 v[132:135], v[156:159], v[202:205], v[132:135]
	v_mfma_f32_16x16x32_bf16 v[124:127], v[170:173], v[202:205], v[124:127]
	v_mfma_f32_16x16x32_bf16 v[116:119], v[156:159], v[224:227], v[116:119]
	v_mfma_f32_16x16x32_bf16 v[108:111], v[170:173], v[224:227], v[108:111]
	s_waitcnt lgkmcnt(0)
	v_mfma_f32_16x16x32_bf16 v[76:79], v[156:159], v[240:243], v[76:79]
	v_mfma_f32_16x16x32_bf16 v[68:71], v[170:173], v[240:243], v[68:71]
	v_mfma_f32_16x16x32_bf16 v[144:147], v[174:177], v[190:193], v[144:147]
	v_mfma_f32_16x16x32_bf16 v[136:139], v[182:185], v[190:193], v[136:139]
	v_mfma_f32_16x16x32_bf16 v[128:131], v[174:177], v[198:201], v[128:131]
	v_mfma_f32_16x16x32_bf16 v[120:123], v[182:185], v[198:201], v[120:123]
	v_mfma_f32_16x16x32_bf16 v[112:115], v[174:177], v[220:223], v[112:115]
	v_mfma_f32_16x16x32_bf16 v[104:107], v[182:185], v[220:223], v[104:107]
	v_mfma_f32_16x16x32_bf16 v[72:75], v[174:177], v[228:231], v[72:75]
	v_mfma_f32_16x16x32_bf16 v[64:67], v[182:185], v[228:231], v[64:67]
	v_mfma_f32_16x16x32_bf16 v[144:147], v[178:181], v[194:197], v[144:147]
	v_mfma_f32_16x16x32_bf16 v[136:139], v[186:189], v[194:197], v[136:139]
	v_mfma_f32_16x16x32_bf16 v[128:131], v[178:181], v[202:205], v[128:131]
	v_mfma_f32_16x16x32_bf16 v[120:123], v[186:189], v[202:205], v[120:123]
	v_mfma_f32_16x16x32_bf16 v[112:115], v[178:181], v[224:227], v[112:115]
	v_mfma_f32_16x16x32_bf16 v[104:107], v[186:189], v[224:227], v[104:107]
	v_mfma_f32_16x16x32_bf16 v[72:75], v[178:181], v[240:243], v[72:75]
	v_mfma_f32_16x16x32_bf16 v[64:67], v[186:189], v[240:243], v[64:67]
	s_barrier
	ds_read_b128 v[190:193], v169 offset:16384
	ds_read_b128 v[194:197], v169 offset:17408
	ds_read_b128 v[198:201], v169 offset:18432
	ds_read_b128 v[202:205], v169 offset:19456
	ds_read_b128 v[220:223], v169 offset:20480
	ds_read_b128 v[224:227], v169 offset:21504
	ds_read_b128 v[228:231], v169 offset:22528
	ds_read_b128 v[240:243], v169 offset:23552
	s_mov_b32 m0, s7
	s_nop 0
	buffer_load_dwordx4 v166, s[28:31], s55 offen lds
	s_add_i32 s57, s55, 0x80000
	s_mov_b32 m0, s8
	s_nop 0
	buffer_load_dwordx4 v167, s[28:31], s55 offen lds
	s_nop 0
	s_mov_b32 m0, s9
	s_nop 0
	buffer_load_dwordx4 v166, s[28:31], s57 offen lds
	s_nop 0
	s_mov_b32 m0, s10
	s_nop 0
	buffer_load_dwordx4 v167, s[28:31], s57 offen lds
	s_nop 0
	s_mov_b32 m0, s6
	s_nop 0
	buffer_load_dwordx4 v166, s[24:27], s56 offen lds
	s_nop 0
	s_mov_b32 m0, s11
	s_nop 0
	buffer_load_dwordx4 v167, s[24:27], s56 offen lds
	s_waitcnt vmcnt(8) lgkmcnt(0)
	s_barrier
	s_waitcnt lgkmcnt(7)
	v_mfma_f32_16x16x32_bf16 v[60:63], v[152:155], v[190:193], v[60:63]
	v_mfma_f32_16x16x32_bf16 v[52:55], v[160:163], v[190:193], v[52:55]
	s_waitcnt lgkmcnt(5)
	v_mfma_f32_16x16x32_bf16 v[44:47], v[152:155], v[198:201], v[44:47]
	v_mfma_f32_16x16x32_bf16 v[36:39], v[160:163], v[198:201], v[36:39]
	s_waitcnt lgkmcnt(3)
	v_mfma_f32_16x16x32_bf16 v[28:31], v[152:155], v[220:223], v[28:31]
	v_mfma_f32_16x16x32_bf16 v[20:23], v[160:163], v[220:223], v[20:23]
	s_waitcnt lgkmcnt(1)
	v_mfma_f32_16x16x32_bf16 v[12:15], v[152:155], v[228:231], v[12:15]
	v_mfma_f32_16x16x32_bf16 v[4:7], v[160:163], v[228:231], v[4:7]
	v_mfma_f32_16x16x32_bf16 v[60:63], v[156:159], v[194:197], v[60:63]
	v_mfma_f32_16x16x32_bf16 v[52:55], v[170:173], v[194:197], v[52:55]
	v_mfma_f32_16x16x32_bf16 v[44:47], v[156:159], v[202:205], v[44:47]
	v_mfma_f32_16x16x32_bf16 v[36:39], v[170:173], v[202:205], v[36:39]
	v_mfma_f32_16x16x32_bf16 v[28:31], v[156:159], v[224:227], v[28:31]
	v_mfma_f32_16x16x32_bf16 v[20:23], v[170:173], v[224:227], v[20:23]
	s_waitcnt lgkmcnt(0)
	v_mfma_f32_16x16x32_bf16 v[12:15], v[156:159], v[240:243], v[12:15]
	v_mfma_f32_16x16x32_bf16 v[4:7], v[170:173], v[240:243], v[4:7]
	v_mfma_f32_16x16x32_bf16 v[56:59], v[174:177], v[190:193], v[56:59]
	v_mfma_f32_16x16x32_bf16 v[48:51], v[182:185], v[190:193], v[48:51]
	v_mfma_f32_16x16x32_bf16 v[40:43], v[174:177], v[198:201], v[40:43]
	v_mfma_f32_16x16x32_bf16 v[32:35], v[182:185], v[198:201], v[32:35]
	v_mfma_f32_16x16x32_bf16 v[24:27], v[174:177], v[220:223], v[24:27]
	v_mfma_f32_16x16x32_bf16 v[16:19], v[182:185], v[220:223], v[16:19]
	v_mfma_f32_16x16x32_bf16 v[8:11], v[174:177], v[228:231], v[8:11]
	v_mfma_f32_16x16x32_bf16 v[0:3], v[182:185], v[228:231], v[0:3]
	v_mfma_f32_16x16x32_bf16 v[56:59], v[178:181], v[194:197], v[56:59]
	v_mfma_f32_16x16x32_bf16 v[48:51], v[186:189], v[194:197], v[48:51]
	v_mfma_f32_16x16x32_bf16 v[40:43], v[178:181], v[202:205], v[40:43]
	v_mfma_f32_16x16x32_bf16 v[32:35], v[186:189], v[202:205], v[32:35]
	v_mfma_f32_16x16x32_bf16 v[24:27], v[178:181], v[224:227], v[24:27]
	v_mfma_f32_16x16x32_bf16 v[16:19], v[186:189], v[224:227], v[16:19]
	v_mfma_f32_16x16x32_bf16 v[8:11], v[178:181], v[240:243], v[8:11]
	v_mfma_f32_16x16x32_bf16 v[0:3], v[186:189], v[240:243], v[0:3]
	s_barrier
	v_add_u32_e32 v164, 0x18000, v168
	ds_read_b128 v[152:155], v164
	ds_read_b128 v[156:159], v164 offset:1024
	ds_read_b128 v[160:163], v164 offset:2048
	ds_read_b128 v[170:173], v164 offset:3072
	v_add_u32_e32 v164, 0x1c000, v168
	ds_read_b128 v[174:177], v164
	ds_read_b128 v[178:181], v164 offset:1024
	ds_read_b128 v[182:185], v164 offset:2048
	ds_read_b128 v[186:189], v164 offset:3072
	ds_read_b128 v[190:193], v169 offset:32768
	ds_read_b128 v[194:197], v169 offset:33792
	ds_read_b128 v[198:201], v169 offset:34816
	ds_read_b128 v[202:205], v169 offset:35840
	ds_read_b128 v[220:223], v169 offset:36864
	ds_read_b128 v[224:227], v169 offset:37888
	ds_read_b128 v[228:231], v169 offset:38912
	ds_read_b128 v[240:243], v169 offset:39936
	s_add_i32 s56, s56, 0x80000
	s_mov_b32 m0, s12
	s_nop 0
	buffer_load_dwordx4 v166, s[24:27], s56 offen lds
	s_nop 0
	s_mov_b32 m0, s13
	s_nop 0
	buffer_load_dwordx4 v167, s[24:27], s56 offen lds
	s_waitcnt vmcnt(8) lgkmcnt(0)
	s_barrier
	s_waitcnt lgkmcnt(7)
	v_mfma_f32_16x16x32_bf16 v[148:151], v[152:155], v[190:193], v[148:151]
	v_mfma_f32_16x16x32_bf16 v[140:143], v[160:163], v[190:193], v[140:143]
	s_waitcnt lgkmcnt(5)
	v_mfma_f32_16x16x32_bf16 v[132:135], v[152:155], v[198:201], v[132:135]
	v_mfma_f32_16x16x32_bf16 v[124:127], v[160:163], v[198:201], v[124:127]
	s_waitcnt lgkmcnt(3)
	v_mfma_f32_16x16x32_bf16 v[116:119], v[152:155], v[220:223], v[116:119]
	v_mfma_f32_16x16x32_bf16 v[108:111], v[160:163], v[220:223], v[108:111]
	s_waitcnt lgkmcnt(1)
	v_mfma_f32_16x16x32_bf16 v[76:79], v[152:155], v[228:231], v[76:79]
	v_mfma_f32_16x16x32_bf16 v[68:71], v[160:163], v[228:231], v[68:71]
	v_mfma_f32_16x16x32_bf16 v[148:151], v[156:159], v[194:197], v[148:151]
	v_mfma_f32_16x16x32_bf16 v[140:143], v[170:173], v[194:197], v[140:143]
	v_mfma_f32_16x16x32_bf16 v[132:135], v[156:159], v[202:205], v[132:135]
	v_mfma_f32_16x16x32_bf16 v[124:127], v[170:173], v[202:205], v[124:127]
	v_mfma_f32_16x16x32_bf16 v[116:119], v[156:159], v[224:227], v[116:119]
	v_mfma_f32_16x16x32_bf16 v[108:111], v[170:173], v[224:227], v[108:111]
	s_waitcnt lgkmcnt(0)
	v_mfma_f32_16x16x32_bf16 v[76:79], v[156:159], v[240:243], v[76:79]
	v_mfma_f32_16x16x32_bf16 v[68:71], v[170:173], v[240:243], v[68:71]
	v_mfma_f32_16x16x32_bf16 v[144:147], v[174:177], v[190:193], v[144:147]
	v_mfma_f32_16x16x32_bf16 v[136:139], v[182:185], v[190:193], v[136:139]
	v_mfma_f32_16x16x32_bf16 v[128:131], v[174:177], v[198:201], v[128:131]
	v_mfma_f32_16x16x32_bf16 v[120:123], v[182:185], v[198:201], v[120:123]
	v_mfma_f32_16x16x32_bf16 v[112:115], v[174:177], v[220:223], v[112:115]
	v_mfma_f32_16x16x32_bf16 v[104:107], v[182:185], v[220:223], v[104:107]
	v_mfma_f32_16x16x32_bf16 v[72:75], v[174:177], v[228:231], v[72:75]
	v_mfma_f32_16x16x32_bf16 v[64:67], v[182:185], v[228:231], v[64:67]
	v_mfma_f32_16x16x32_bf16 v[144:147], v[178:181], v[194:197], v[144:147]
	v_mfma_f32_16x16x32_bf16 v[136:139], v[186:189], v[194:197], v[136:139]
	v_mfma_f32_16x16x32_bf16 v[128:131], v[178:181], v[202:205], v[128:131]
	v_mfma_f32_16x16x32_bf16 v[120:123], v[186:189], v[202:205], v[120:123]
	v_mfma_f32_16x16x32_bf16 v[112:115], v[178:181], v[224:227], v[112:115]
	v_mfma_f32_16x16x32_bf16 v[104:107], v[186:189], v[224:227], v[104:107]
	v_mfma_f32_16x16x32_bf16 v[72:75], v[178:181], v[240:243], v[72:75]
	v_mfma_f32_16x16x32_bf16 v[64:67], v[186:189], v[240:243], v[64:67]
	s_barrier
	ds_read_b128 v[190:193], v169 offset:49152
	ds_read_b128 v[194:197], v169 offset:50176
	ds_read_b128 v[198:201], v169 offset:51200
	ds_read_b128 v[202:205], v169 offset:52224
	ds_read_b128 v[220:223], v169 offset:53248
	ds_read_b128 v[224:227], v169 offset:54272
	ds_read_b128 v[228:231], v169 offset:55296
	ds_read_b128 v[240:243], v169 offset:56320
	s_or_b32 s56, s55, 0x4000
	s_mov_b32 m0, s16
	s_nop 0
	buffer_load_dwordx4 v166, s[28:31], s56 offen lds
	s_add_i32 s55, s55, 0x84000
	s_mov_b32 m0, s17
	s_nop 0
	buffer_load_dwordx4 v167, s[28:31], s56 offen lds
	s_nop 0
	s_mov_b32 m0, s34
	s_nop 0
	buffer_load_dwordx4 v166, s[28:31], s55 offen lds
	s_nop 0
	s_mov_b32 m0, s40
	s_nop 0
	buffer_load_dwordx4 v167, s[28:31], s55 offen lds
	s_nop 0
	s_mov_b32 m0, s18
	s_nop 0
	buffer_load_dwordx4 v166, s[24:27], s53 offen lds
	s_nop 0
	s_mov_b32 m0, s19
	s_nop 0
	buffer_load_dwordx4 v167, s[24:27], s53 offen lds
	s_waitcnt vmcnt(8) lgkmcnt(0)
	s_barrier
	s_waitcnt lgkmcnt(7)
	v_mfma_f32_16x16x32_bf16 v[60:63], v[152:155], v[190:193], v[60:63]
	v_mfma_f32_16x16x32_bf16 v[52:55], v[160:163], v[190:193], v[52:55]
	s_waitcnt lgkmcnt(5)
	v_mfma_f32_16x16x32_bf16 v[44:47], v[152:155], v[198:201], v[44:47]
	v_mfma_f32_16x16x32_bf16 v[36:39], v[160:163], v[198:201], v[36:39]
	s_waitcnt lgkmcnt(3)
	v_mfma_f32_16x16x32_bf16 v[28:31], v[152:155], v[220:223], v[28:31]
	v_mfma_f32_16x16x32_bf16 v[20:23], v[160:163], v[220:223], v[20:23]
	s_waitcnt lgkmcnt(1)
	v_mfma_f32_16x16x32_bf16 v[12:15], v[152:155], v[228:231], v[12:15]
	v_mfma_f32_16x16x32_bf16 v[4:7], v[160:163], v[228:231], v[4:7]
	v_mfma_f32_16x16x32_bf16 v[60:63], v[156:159], v[194:197], v[60:63]
	v_mfma_f32_16x16x32_bf16 v[52:55], v[170:173], v[194:197], v[52:55]
	v_mfma_f32_16x16x32_bf16 v[44:47], v[156:159], v[202:205], v[44:47]
	v_mfma_f32_16x16x32_bf16 v[36:39], v[170:173], v[202:205], v[36:39]
	v_mfma_f32_16x16x32_bf16 v[28:31], v[156:159], v[224:227], v[28:31]
	v_mfma_f32_16x16x32_bf16 v[20:23], v[170:173], v[224:227], v[20:23]
	s_waitcnt lgkmcnt(0)
	v_mfma_f32_16x16x32_bf16 v[12:15], v[156:159], v[240:243], v[12:15]
	v_mfma_f32_16x16x32_bf16 v[4:7], v[170:173], v[240:243], v[4:7]
	v_mfma_f32_16x16x32_bf16 v[56:59], v[174:177], v[190:193], v[56:59]
	v_mfma_f32_16x16x32_bf16 v[48:51], v[182:185], v[190:193], v[48:51]
	v_mfma_f32_16x16x32_bf16 v[40:43], v[174:177], v[198:201], v[40:43]
	v_mfma_f32_16x16x32_bf16 v[32:35], v[182:185], v[198:201], v[32:35]
	v_mfma_f32_16x16x32_bf16 v[24:27], v[174:177], v[220:223], v[24:27]
	v_mfma_f32_16x16x32_bf16 v[16:19], v[182:185], v[220:223], v[16:19]
	v_mfma_f32_16x16x32_bf16 v[8:11], v[174:177], v[228:231], v[8:11]
	v_mfma_f32_16x16x32_bf16 v[0:3], v[182:185], v[228:231], v[0:3]
	v_mfma_f32_16x16x32_bf16 v[56:59], v[178:181], v[194:197], v[56:59]
	v_mfma_f32_16x16x32_bf16 v[48:51], v[186:189], v[194:197], v[48:51]
	v_mfma_f32_16x16x32_bf16 v[40:43], v[178:181], v[202:205], v[40:43]
	v_mfma_f32_16x16x32_bf16 v[32:35], v[186:189], v[202:205], v[32:35]
	v_mfma_f32_16x16x32_bf16 v[24:27], v[178:181], v[224:227], v[24:27]
	v_mfma_f32_16x16x32_bf16 v[16:19], v[186:189], v[224:227], v[16:19]
	v_mfma_f32_16x16x32_bf16 v[8:11], v[178:181], v[240:243], v[8:11]
	v_mfma_f32_16x16x32_bf16 v[0:3], v[186:189], v[240:243], v[0:3]
	s_barrier
	s_add_i32 s52, s52, 2
	s_add_i32 s37, s37, 0x8000
	s_add_i32 s51, s51, 0x8000
	s_cmp_gt_u32 s52, 29
	s_cbranch_scc0 .LBB0_795

.Lnb_p6:
	s_add_i32 s11, s8, 0xffea4000
	s_cmpk_eq_i32 s10, 0x54
	s_cselect_b32 s13, s6, s11
	s_cselect_b32 s12, s7, s9
	s_or_b32 s11, s13, 0x4000
	s_mov_b32 m0, s87
	s_nop 0
	buffer_load_dwordx4 v220, s[20:23], s8 offen lds
	s_nop 0
	s_mov_b32 m0, s89
	s_nop 0
	buffer_load_dwordx4 v221, s[20:23], s8 offen lds
	s_waitcnt vmcnt(24) lgkmcnt(0)
	s_barrier
	s_waitcnt lgkmcnt(7)
	v_mfma_f32_16x16x32_bf16 v[164:167], v[128:131], v[184:187], 0
	v_mfma_f32_16x16x32_bf16 v[160:163], v[152:155], v[184:187], 0
	s_waitcnt lgkmcnt(5)
	v_mfma_f32_16x16x32_bf16 v[136:139], v[128:131], v[192:195], 0
	v_mfma_f32_16x16x32_bf16 v[132:135], v[152:155], v[192:195], 0
	s_waitcnt lgkmcnt(3)
	v_mfma_f32_16x16x32_bf16 v[116:119], v[128:131], v[200:203], 0
	v_mfma_f32_16x16x32_bf16 v[112:115], v[152:155], v[200:203], 0
	s_waitcnt lgkmcnt(1)
	v_mfma_f32_16x16x32_bf16 v[76:79], v[128:131], v[224:227], 0
	v_mfma_f32_16x16x32_bf16 v[72:75], v[152:155], v[224:227], 0
	v_mfma_f32_16x16x32_bf16 v[164:167], v[140:143], v[188:191], v[164:167]
	v_mfma_f32_16x16x32_bf16 v[160:163], v[156:159], v[188:191], v[160:163]
	v_mfma_f32_16x16x32_bf16 v[136:139], v[140:143], v[196:199], v[136:139]
	v_mfma_f32_16x16x32_bf16 v[132:135], v[156:159], v[196:199], v[132:135]
	v_mfma_f32_16x16x32_bf16 v[116:119], v[140:143], v[204:207], v[116:119]
	v_mfma_f32_16x16x32_bf16 v[112:115], v[156:159], v[204:207], v[112:115]
	s_waitcnt lgkmcnt(0)
	v_mfma_f32_16x16x32_bf16 v[76:79], v[140:143], v[228:231], v[76:79]
	v_mfma_f32_16x16x32_bf16 v[72:75], v[156:159], v[228:231], v[72:75]
	v_mfma_f32_16x16x32_bf16 v[148:151], v[168:171], v[184:187], 0
	v_mfma_f32_16x16x32_bf16 v[144:147], v[176:179], v[184:187], 0
	v_mfma_f32_16x16x32_bf16 v[124:127], v[168:171], v[192:195], 0
	v_mfma_f32_16x16x32_bf16 v[120:123], v[176:179], v[192:195], 0
	v_mfma_f32_16x16x32_bf16 v[108:111], v[168:171], v[200:203], 0
	v_mfma_f32_16x16x32_bf16 v[104:107], v[176:179], v[200:203], 0
	v_mfma_f32_16x16x32_bf16 v[68:71], v[168:171], v[224:227], 0
	v_mfma_f32_16x16x32_bf16 v[64:67], v[176:179], v[224:227], 0
	v_mfma_f32_16x16x32_bf16 v[148:151], v[172:175], v[188:191], v[148:151]
	v_mfma_f32_16x16x32_bf16 v[144:147], v[180:183], v[188:191], v[144:147]
	v_mfma_f32_16x16x32_bf16 v[124:127], v[172:175], v[196:199], v[124:127]
	v_mfma_f32_16x16x32_bf16 v[120:123], v[180:183], v[196:199], v[120:123]
	v_mfma_f32_16x16x32_bf16 v[108:111], v[172:175], v[204:207], v[108:111]
	v_mfma_f32_16x16x32_bf16 v[104:107], v[180:183], v[204:207], v[104:107]
	v_mfma_f32_16x16x32_bf16 v[68:71], v[172:175], v[228:231], v[68:71]
	v_mfma_f32_16x16x32_bf16 v[64:67], v[180:183], v[228:231], v[64:67]
	s_barrier
	ds_read_b128 v[184:187], v223 offset:16384
	ds_read_b128 v[188:191], v223 offset:17408
	ds_read_b128 v[192:195], v223 offset:18432
	ds_read_b128 v[196:199], v223 offset:19456
	ds_read_b128 v[200:203], v223 offset:20480
	ds_read_b128 v[204:207], v223 offset:21504
	ds_read_b128 v[224:227], v223 offset:22528
	ds_read_b128 v[228:231], v223 offset:23552
	s_mov_b32 m0, s51
	s_nop 0
	buffer_load_dwordx4 v220, s[52:55], s12 offen lds
	s_add_i32 s14, s12, 0x160000
	s_mov_b32 m0, s74
	s_nop 0
	buffer_load_dwordx4 v221, s[52:55], s12 offen lds
	s_nop 0
	s_mov_b32 m0, s75
	s_nop 0
	buffer_load_dwordx4 v220, s[52:55], s14 offen lds
	s_nop 0
	s_mov_b32 m0, s76
	s_nop 0
	buffer_load_dwordx4 v221, s[52:55], s14 offen lds
	s_nop 0
	s_mov_b32 m0, s31
	s_nop 0
	buffer_load_dwordx4 v220, s[20:23], s13 offen lds
	s_nop 0
	s_mov_b32 m0, s77
	s_nop 0
	buffer_load_dwordx4 v221, s[20:23], s13 offen lds
	s_waitcnt vmcnt(24) lgkmcnt(0)
	s_barrier
	s_waitcnt lgkmcnt(7)
	v_mfma_f32_16x16x32_bf16 v[60:63], v[128:131], v[184:187], 0
	v_mfma_f32_16x16x32_bf16 v[56:59], v[152:155], v[184:187], 0
	s_waitcnt lgkmcnt(5)
	v_mfma_f32_16x16x32_bf16 v[44:47], v[128:131], v[192:195], 0
	v_mfma_f32_16x16x32_bf16 v[40:43], v[152:155], v[192:195], 0
	s_waitcnt lgkmcnt(3)
	v_mfma_f32_16x16x32_bf16 v[28:31], v[128:131], v[200:203], 0
	v_mfma_f32_16x16x32_bf16 v[24:27], v[152:155], v[200:203], 0
	s_waitcnt lgkmcnt(1)
	v_mfma_f32_16x16x32_bf16 v[12:15], v[128:131], v[224:227], 0
	v_mfma_f32_16x16x32_bf16 v[8:11], v[152:155], v[224:227], 0
	v_mfma_f32_16x16x32_bf16 v[60:63], v[140:143], v[188:191], v[60:63]
	v_mfma_f32_16x16x32_bf16 v[56:59], v[156:159], v[188:191], v[56:59]
	v_mfma_f32_16x16x32_bf16 v[44:47], v[140:143], v[196:199], v[44:47]
	v_mfma_f32_16x16x32_bf16 v[40:43], v[156:159], v[196:199], v[40:43]
	v_mfma_f32_16x16x32_bf16 v[28:31], v[140:143], v[204:207], v[28:31]
	v_mfma_f32_16x16x32_bf16 v[24:27], v[156:159], v[204:207], v[24:27]
	s_waitcnt lgkmcnt(0)
	v_mfma_f32_16x16x32_bf16 v[12:15], v[140:143], v[228:231], v[12:15]
	v_mfma_f32_16x16x32_bf16 v[8:11], v[156:159], v[228:231], v[8:11]
	v_mfma_f32_16x16x32_bf16 v[52:55], v[168:171], v[184:187], 0
	v_mfma_f32_16x16x32_bf16 v[48:51], v[176:179], v[184:187], 0
	v_mfma_f32_16x16x32_bf16 v[36:39], v[168:171], v[192:195], 0
	v_mfma_f32_16x16x32_bf16 v[32:35], v[176:179], v[192:195], 0
	v_mfma_f32_16x16x32_bf16 v[20:23], v[168:171], v[200:203], 0
	v_mfma_f32_16x16x32_bf16 v[16:19], v[176:179], v[200:203], 0
	v_mfma_f32_16x16x32_bf16 v[4:7], v[168:171], v[224:227], 0
	v_mfma_f32_16x16x32_bf16 v[0:3], v[176:179], v[224:227], 0
	v_mfma_f32_16x16x32_bf16 v[52:55], v[172:175], v[188:191], v[52:55]
	v_mfma_f32_16x16x32_bf16 v[48:51], v[180:183], v[188:191], v[48:51]
	v_mfma_f32_16x16x32_bf16 v[36:39], v[172:175], v[196:199], v[36:39]
	v_mfma_f32_16x16x32_bf16 v[32:35], v[180:183], v[196:199], v[32:35]
	v_mfma_f32_16x16x32_bf16 v[20:23], v[172:175], v[204:207], v[20:23]
	v_mfma_f32_16x16x32_bf16 v[16:19], v[180:183], v[204:207], v[16:19]
	v_mfma_f32_16x16x32_bf16 v[4:7], v[172:175], v[228:231], v[4:7]
	v_mfma_f32_16x16x32_bf16 v[0:3], v[180:183], v[228:231], v[0:3]
	s_barrier
	v_add_u32_e32 v156, 0x18000, v222
	v_add_u32_e32 v180, 0x1c000, v222
	ds_read_b128 v[128:131], v156
	ds_read_b128 v[140:143], v156 offset:1024
	ds_read_b128 v[152:155], v156 offset:2048
	ds_read_b128 v[156:159], v156 offset:3072
	ds_read_b128 v[168:171], v180
	ds_read_b128 v[172:175], v180 offset:1024
	ds_read_b128 v[176:179], v180 offset:2048
	ds_read_b128 v[180:183], v180 offset:3072
	ds_read_b128 v[184:187], v223 offset:32768
	ds_read_b128 v[188:191], v223 offset:33792
	ds_read_b128 v[192:195], v223 offset:34816
	ds_read_b128 v[196:199], v223 offset:35840
	ds_read_b128 v[200:203], v223 offset:36864
	ds_read_b128 v[204:207], v223 offset:37888
	ds_read_b128 v[224:227], v223 offset:38912
	ds_read_b128 v[228:231], v223 offset:39936
	s_add_i32 s13, s13, 0x160000
	s_mov_b32 m0, s78
	s_nop 0
	buffer_load_dwordx4 v220, s[20:23], s13 offen lds
	s_nop 0
	s_mov_b32 m0, s79
	s_nop 0
	buffer_load_dwordx4 v221, s[20:23], s13 offen lds
	s_waitcnt vmcnt(8) lgkmcnt(0)
	s_barrier
	s_waitcnt lgkmcnt(7)
	v_mfma_f32_16x16x32_bf16 v[164:167], v[128:131], v[184:187], v[164:167]
	v_mfma_f32_16x16x32_bf16 v[160:163], v[152:155], v[184:187], v[160:163]
	s_waitcnt lgkmcnt(5)
	v_mfma_f32_16x16x32_bf16 v[136:139], v[128:131], v[192:195], v[136:139]
	v_mfma_f32_16x16x32_bf16 v[132:135], v[152:155], v[192:195], v[132:135]
	s_waitcnt lgkmcnt(3)
	v_mfma_f32_16x16x32_bf16 v[116:119], v[128:131], v[200:203], v[116:119]
	v_mfma_f32_16x16x32_bf16 v[112:115], v[152:155], v[200:203], v[112:115]
	s_waitcnt lgkmcnt(1)
	v_mfma_f32_16x16x32_bf16 v[76:79], v[128:131], v[224:227], v[76:79]
	v_mfma_f32_16x16x32_bf16 v[72:75], v[152:155], v[224:227], v[72:75]
	v_mfma_f32_16x16x32_bf16 v[164:167], v[140:143], v[188:191], v[164:167]
	v_mfma_f32_16x16x32_bf16 v[160:163], v[156:159], v[188:191], v[160:163]
	v_mfma_f32_16x16x32_bf16 v[136:139], v[140:143], v[196:199], v[136:139]
	v_mfma_f32_16x16x32_bf16 v[132:135], v[156:159], v[196:199], v[132:135]
	v_mfma_f32_16x16x32_bf16 v[116:119], v[140:143], v[204:207], v[116:119]
	v_mfma_f32_16x16x32_bf16 v[112:115], v[156:159], v[204:207], v[112:115]
	s_waitcnt lgkmcnt(0)
	v_mfma_f32_16x16x32_bf16 v[76:79], v[140:143], v[228:231], v[76:79]
	v_mfma_f32_16x16x32_bf16 v[72:75], v[156:159], v[228:231], v[72:75]
	v_mfma_f32_16x16x32_bf16 v[148:151], v[168:171], v[184:187], v[148:151]
	v_mfma_f32_16x16x32_bf16 v[144:147], v[176:179], v[184:187], v[144:147]
	v_mfma_f32_16x16x32_bf16 v[124:127], v[168:171], v[192:195], v[124:127]
	v_mfma_f32_16x16x32_bf16 v[120:123], v[176:179], v[192:195], v[120:123]
	v_mfma_f32_16x16x32_bf16 v[108:111], v[168:171], v[200:203], v[108:111]
	v_mfma_f32_16x16x32_bf16 v[104:107], v[176:179], v[200:203], v[104:107]
	v_mfma_f32_16x16x32_bf16 v[68:71], v[168:171], v[224:227], v[68:71]
	v_mfma_f32_16x16x32_bf16 v[64:67], v[176:179], v[224:227], v[64:67]
	v_mfma_f32_16x16x32_bf16 v[148:151], v[172:175], v[188:191], v[148:151]
	v_mfma_f32_16x16x32_bf16 v[144:147], v[180:183], v[188:191], v[144:147]
	v_mfma_f32_16x16x32_bf16 v[124:127], v[172:175], v[196:199], v[124:127]
	v_mfma_f32_16x16x32_bf16 v[120:123], v[180:183], v[196:199], v[120:123]
	v_mfma_f32_16x16x32_bf16 v[108:111], v[172:175], v[204:207], v[108:111]
	v_mfma_f32_16x16x32_bf16 v[104:107], v[180:183], v[204:207], v[104:107]
	v_mfma_f32_16x16x32_bf16 v[68:71], v[172:175], v[228:231], v[68:71]
	v_mfma_f32_16x16x32_bf16 v[64:67], v[180:183], v[228:231], v[64:67]
	s_barrier
	ds_read_b128 v[184:187], v223 offset:49152
	ds_read_b128 v[188:191], v223 offset:50176
	ds_read_b128 v[192:195], v223 offset:51200
	ds_read_b128 v[196:199], v223 offset:52224
	ds_read_b128 v[200:203], v223 offset:53248
	ds_read_b128 v[204:207], v223 offset:54272
	ds_read_b128 v[224:227], v223 offset:55296
	ds_read_b128 v[228:231], v223 offset:56320
	s_or_b32 s13, s12, 0x4000
	s_mov_b32 m0, s34
	s_nop 0
	buffer_load_dwordx4 v220, s[52:55], s13 offen lds
	s_add_i32 s12, s12, 0x164000
	s_mov_b32 m0, s82
	s_nop 0
	buffer_load_dwordx4 v221, s[52:55], s13 offen lds
	s_nop 0
	s_mov_b32 m0, s85
	s_nop 0
	buffer_load_dwordx4 v220, s[52:55], s12 offen lds
	s_nop 0
	s_mov_b32 m0, s86
	s_nop 0
	buffer_load_dwordx4 v221, s[52:55], s12 offen lds
	s_nop 0
	s_mov_b32 m0, s83
	s_nop 0
	buffer_load_dwordx4 v220, s[20:23], s11 offen lds
	s_nop 0
	s_mov_b32 m0, s84
	s_nop 0
	buffer_load_dwordx4 v221, s[20:23], s11 offen lds
	s_waitcnt vmcnt(8) lgkmcnt(0)
	s_barrier
	s_waitcnt lgkmcnt(7)
	v_mfma_f32_16x16x32_bf16 v[60:63], v[128:131], v[184:187], v[60:63]
	v_mfma_f32_16x16x32_bf16 v[56:59], v[152:155], v[184:187], v[56:59]
	s_waitcnt lgkmcnt(5)
	v_mfma_f32_16x16x32_bf16 v[44:47], v[128:131], v[192:195], v[44:47]
	v_mfma_f32_16x16x32_bf16 v[40:43], v[152:155], v[192:195], v[40:43]
	s_waitcnt lgkmcnt(3)
	v_mfma_f32_16x16x32_bf16 v[28:31], v[128:131], v[200:203], v[28:31]
	v_mfma_f32_16x16x32_bf16 v[24:27], v[152:155], v[200:203], v[24:27]
	s_waitcnt lgkmcnt(1)
	v_mfma_f32_16x16x32_bf16 v[12:15], v[128:131], v[224:227], v[12:15]
	v_mfma_f32_16x16x32_bf16 v[8:11], v[152:155], v[224:227], v[8:11]
	v_mfma_f32_16x16x32_bf16 v[60:63], v[140:143], v[188:191], v[60:63]
	v_mfma_f32_16x16x32_bf16 v[56:59], v[156:159], v[188:191], v[56:59]
	v_mfma_f32_16x16x32_bf16 v[44:47], v[140:143], v[196:199], v[44:47]
	v_mfma_f32_16x16x32_bf16 v[40:43], v[156:159], v[196:199], v[40:43]
	v_mfma_f32_16x16x32_bf16 v[28:31], v[140:143], v[204:207], v[28:31]
	v_mfma_f32_16x16x32_bf16 v[24:27], v[156:159], v[204:207], v[24:27]
	s_waitcnt lgkmcnt(0)
	v_mfma_f32_16x16x32_bf16 v[12:15], v[140:143], v[228:231], v[12:15]
	v_mfma_f32_16x16x32_bf16 v[8:11], v[156:159], v[228:231], v[8:11]
	v_mfma_f32_16x16x32_bf16 v[52:55], v[168:171], v[184:187], v[52:55]
	v_mfma_f32_16x16x32_bf16 v[48:51], v[176:179], v[184:187], v[48:51]
	v_mfma_f32_16x16x32_bf16 v[36:39], v[168:171], v[192:195], v[36:39]
	v_mfma_f32_16x16x32_bf16 v[32:35], v[176:179], v[192:195], v[32:35]
	v_mfma_f32_16x16x32_bf16 v[20:23], v[168:171], v[200:203], v[20:23]
	v_mfma_f32_16x16x32_bf16 v[16:19], v[176:179], v[200:203], v[16:19]
	v_mfma_f32_16x16x32_bf16 v[4:7], v[168:171], v[224:227], v[4:7]
	v_mfma_f32_16x16x32_bf16 v[0:3], v[176:179], v[224:227], v[0:3]
	v_mfma_f32_16x16x32_bf16 v[52:55], v[172:175], v[188:191], v[52:55]
	v_mfma_f32_16x16x32_bf16 v[48:51], v[180:183], v[188:191], v[48:51]
	v_mfma_f32_16x16x32_bf16 v[36:39], v[172:175], v[196:199], v[36:39]
	v_mfma_f32_16x16x32_bf16 v[32:35], v[180:183], v[196:199], v[32:35]
	v_mfma_f32_16x16x32_bf16 v[20:23], v[172:175], v[204:207], v[20:23]
	v_mfma_f32_16x16x32_bf16 v[16:19], v[180:183], v[204:207], v[16:19]
	v_mfma_f32_16x16x32_bf16 v[4:7], v[172:175], v[228:231], v[4:7]
	v_mfma_f32_16x16x32_bf16 v[0:3], v[180:183], v[228:231], v[0:3]
	s_barrier
	s_add_i32 s10, s10, 2
	s_add_i32 s8, s8, 0x8000
	s_add_i32 s9, s9, 0x8000
.LBB0_885:
	v_add_u32_e32 v156, 0x10000, v222
	v_add_u32_e32 v180, 0x14000, v222
	ds_read_b128 v[128:131], v156
	ds_read_b128 v[140:143], v156 offset:1024
	ds_read_b128 v[152:155], v156 offset:2048
	ds_read_b128 v[156:159], v156 offset:3072
	ds_read_b128 v[168:171], v180
	ds_read_b128 v[172:175], v180 offset:1024
	ds_read_b128 v[176:179], v180 offset:2048
	ds_read_b128 v[180:183], v180 offset:3072
	s_add_i32 s11, s8, 0xffea4000
	s_cmpk_eq_i32 s10, 0x54
	s_cselect_b32 s13, s6, s11
	s_cselect_b32 s12, s7, s9
	s_or_b32 s11, s13, 0x4000
	ds_read_b128 v[184:187], v223
	ds_read_b128 v[188:191], v223 offset:1024
	ds_read_b128 v[192:195], v223 offset:2048
	ds_read_b128 v[196:199], v223 offset:3072
	ds_read_b128 v[200:203], v223 offset:4096
	ds_read_b128 v[204:207], v223 offset:5120
	ds_read_b128 v[224:227], v223 offset:6144
	ds_read_b128 v[228:231], v223 offset:7168
	s_mov_b32 m0, s87
	s_nop 0
	buffer_load_dwordx4 v220, s[20:23], s8 offen lds
	s_nop 0
	s_mov_b32 m0, s89
	s_nop 0
	buffer_load_dwordx4 v221, s[20:23], s8 offen lds
	s_waitcnt vmcnt(8) lgkmcnt(0)
	s_barrier
	s_waitcnt lgkmcnt(7)
	v_mfma_f32_16x16x32_bf16 v[164:167], v[128:131], v[184:187], v[164:167]
	v_mfma_f32_16x16x32_bf16 v[160:163], v[152:155], v[184:187], v[160:163]
	s_waitcnt lgkmcnt(5)
	v_mfma_f32_16x16x32_bf16 v[136:139], v[128:131], v[192:195], v[136:139]
	v_mfma_f32_16x16x32_bf16 v[132:135], v[152:155], v[192:195], v[132:135]
	s_waitcnt lgkmcnt(3)
	v_mfma_f32_16x16x32_bf16 v[116:119], v[128:131], v[200:203], v[116:119]
	v_mfma_f32_16x16x32_bf16 v[112:115], v[152:155], v[200:203], v[112:115]
	s_waitcnt lgkmcnt(1)
	v_mfma_f32_16x16x32_bf16 v[76:79], v[128:131], v[224:227], v[76:79]
	v_mfma_f32_16x16x32_bf16 v[72:75], v[152:155], v[224:227], v[72:75]
	v_mfma_f32_16x16x32_bf16 v[164:167], v[140:143], v[188:191], v[164:167]
	v_mfma_f32_16x16x32_bf16 v[160:163], v[156:159], v[188:191], v[160:163]
	v_mfma_f32_16x16x32_bf16 v[136:139], v[140:143], v[196:199], v[136:139]
	v_mfma_f32_16x16x32_bf16 v[132:135], v[156:159], v[196:199], v[132:135]
	v_mfma_f32_16x16x32_bf16 v[116:119], v[140:143], v[204:207], v[116:119]
	v_mfma_f32_16x16x32_bf16 v[112:115], v[156:159], v[204:207], v[112:115]
	s_waitcnt lgkmcnt(0)
	v_mfma_f32_16x16x32_bf16 v[76:79], v[140:143], v[228:231], v[76:79]
	v_mfma_f32_16x16x32_bf16 v[72:75], v[156:159], v[228:231], v[72:75]
	v_mfma_f32_16x16x32_bf16 v[148:151], v[168:171], v[184:187], v[148:151]
	v_mfma_f32_16x16x32_bf16 v[144:147], v[176:179], v[184:187], v[144:147]
	v_mfma_f32_16x16x32_bf16 v[124:127], v[168:171], v[192:195], v[124:127]
	v_mfma_f32_16x16x32_bf16 v[120:123], v[176:179], v[192:195], v[120:123]
	v_mfma_f32_16x16x32_bf16 v[108:111], v[168:171], v[200:203], v[108:111]
	v_mfma_f32_16x16x32_bf16 v[104:107], v[176:179], v[200:203], v[104:107]
	v_mfma_f32_16x16x32_bf16 v[68:71], v[168:171], v[224:227], v[68:71]
	v_mfma_f32_16x16x32_bf16 v[64:67], v[176:179], v[224:227], v[64:67]
	v_mfma_f32_16x16x32_bf16 v[148:151], v[172:175], v[188:191], v[148:151]
	v_mfma_f32_16x16x32_bf16 v[144:147], v[180:183], v[188:191], v[144:147]
	v_mfma_f32_16x16x32_bf16 v[124:127], v[172:175], v[196:199], v[124:127]
	v_mfma_f32_16x16x32_bf16 v[120:123], v[180:183], v[196:199], v[120:123]
	v_mfma_f32_16x16x32_bf16 v[108:111], v[172:175], v[204:207], v[108:111]
	v_mfma_f32_16x16x32_bf16 v[104:107], v[180:183], v[204:207], v[104:107]
	v_mfma_f32_16x16x32_bf16 v[68:71], v[172:175], v[228:231], v[68:71]
	v_mfma_f32_16x16x32_bf16 v[64:67], v[180:183], v[228:231], v[64:67]
	s_barrier
	ds_read_b128 v[184:187], v223 offset:16384
	ds_read_b128 v[188:191], v223 offset:17408
	ds_read_b128 v[192:195], v223 offset:18432
	ds_read_b128 v[196:199], v223 offset:19456
	ds_read_b128 v[200:203], v223 offset:20480
	ds_read_b128 v[204:207], v223 offset:21504
	ds_read_b128 v[224:227], v223 offset:22528
	ds_read_b128 v[228:231], v223 offset:23552
	s_mov_b32 m0, s51
	s_nop 0
	buffer_load_dwordx4 v220, s[52:55], s12 offen lds
	s_add_i32 s14, s12, 0x160000
	s_mov_b32 m0, s74
	s_nop 0
	buffer_load_dwordx4 v221, s[52:55], s12 offen lds
	s_nop 0
	s_mov_b32 m0, s75
	s_nop 0
	buffer_load_dwordx4 v220, s[52:55], s14 offen lds
	s_nop 0
	s_mov_b32 m0, s76
	s_nop 0
	buffer_load_dwordx4 v221, s[52:55], s14 offen lds
	s_nop 0
	s_mov_b32 m0, s31
	s_nop 0
	buffer_load_dwordx4 v220, s[20:23], s13 offen lds
	s_nop 0
	s_mov_b32 m0, s77
	s_nop 0
	buffer_load_dwordx4 v221, s[20:23], s13 offen lds
	s_waitcnt vmcnt(8) lgkmcnt(0)
	s_barrier
	s_waitcnt lgkmcnt(7)
	v_mfma_f32_16x16x32_bf16 v[60:63], v[128:131], v[184:187], v[60:63]
	v_mfma_f32_16x16x32_bf16 v[56:59], v[152:155], v[184:187], v[56:59]
	s_waitcnt lgkmcnt(5)
	v_mfma_f32_16x16x32_bf16 v[44:47], v[128:131], v[192:195], v[44:47]
	v_mfma_f32_16x16x32_bf16 v[40:43], v[152:155], v[192:195], v[40:43]
	s_waitcnt lgkmcnt(3)
	v_mfma_f32_16x16x32_bf16 v[28:31], v[128:131], v[200:203], v[28:31]
	v_mfma_f32_16x16x32_bf16 v[24:27], v[152:155], v[200:203], v[24:27]
	s_waitcnt lgkmcnt(1)
	v_mfma_f32_16x16x32_bf16 v[12:15], v[128:131], v[224:227], v[12:15]
	v_mfma_f32_16x16x32_bf16 v[8:11], v[152:155], v[224:227], v[8:11]
	v_mfma_f32_16x16x32_bf16 v[60:63], v[140:143], v[188:191], v[60:63]
	v_mfma_f32_16x16x32_bf16 v[56:59], v[156:159], v[188:191], v[56:59]
	v_mfma_f32_16x16x32_bf16 v[44:47], v[140:143], v[196:199], v[44:47]
	v_mfma_f32_16x16x32_bf16 v[40:43], v[156:159], v[196:199], v[40:43]
	v_mfma_f32_16x16x32_bf16 v[28:31], v[140:143], v[204:207], v[28:31]
	v_mfma_f32_16x16x32_bf16 v[24:27], v[156:159], v[204:207], v[24:27]
	s_waitcnt lgkmcnt(0)
	v_mfma_f32_16x16x32_bf16 v[12:15], v[140:143], v[228:231], v[12:15]
	v_mfma_f32_16x16x32_bf16 v[8:11], v[156:159], v[228:231], v[8:11]
	v_mfma_f32_16x16x32_bf16 v[52:55], v[168:171], v[184:187], v[52:55]
	v_mfma_f32_16x16x32_bf16 v[48:51], v[176:179], v[184:187], v[48:51]
	v_mfma_f32_16x16x32_bf16 v[36:39], v[168:171], v[192:195], v[36:39]
	v_mfma_f32_16x16x32_bf16 v[32:35], v[176:179], v[192:195], v[32:35]
	v_mfma_f32_16x16x32_bf16 v[20:23], v[168:171], v[200:203], v[20:23]
	v_mfma_f32_16x16x32_bf16 v[16:19], v[176:179], v[200:203], v[16:19]
	v_mfma_f32_16x16x32_bf16 v[4:7], v[168:171], v[224:227], v[4:7]
	v_mfma_f32_16x16x32_bf16 v[0:3], v[176:179], v[224:227], v[0:3]
	v_mfma_f32_16x16x32_bf16 v[52:55], v[172:175], v[188:191], v[52:55]
	v_mfma_f32_16x16x32_bf16 v[48:51], v[180:183], v[188:191], v[48:51]
	v_mfma_f32_16x16x32_bf16 v[36:39], v[172:175], v[196:199], v[36:39]
	v_mfma_f32_16x16x32_bf16 v[32:35], v[180:183], v[196:199], v[32:35]
	v_mfma_f32_16x16x32_bf16 v[20:23], v[172:175], v[204:207], v[20:23]
	v_mfma_f32_16x16x32_bf16 v[16:19], v[180:183], v[204:207], v[16:19]
	v_mfma_f32_16x16x32_bf16 v[4:7], v[172:175], v[228:231], v[4:7]
	v_mfma_f32_16x16x32_bf16 v[0:3], v[180:183], v[228:231], v[0:3]
	s_barrier
	v_add_u32_e32 v156, 0x18000, v222
	v_add_u32_e32 v180, 0x1c000, v222
	ds_read_b128 v[128:131], v156
	ds_read_b128 v[140:143], v156 offset:1024
	ds_read_b128 v[152:155], v156 offset:2048
	ds_read_b128 v[156:159], v156 offset:3072
	ds_read_b128 v[168:171], v180
	ds_read_b128 v[172:175], v180 offset:1024
	ds_read_b128 v[176:179], v180 offset:2048
	ds_read_b128 v[180:183], v180 offset:3072
	ds_read_b128 v[184:187], v223 offset:32768
	ds_read_b128 v[188:191], v223 offset:33792
	ds_read_b128 v[192:195], v223 offset:34816
	ds_read_b128 v[196:199], v223 offset:35840
	ds_read_b128 v[200:203], v223 offset:36864
	ds_read_b128 v[204:207], v223 offset:37888
	ds_read_b128 v[224:227], v223 offset:38912
	ds_read_b128 v[228:231], v223 offset:39936
	s_add_i32 s13, s13, 0x160000
	s_mov_b32 m0, s78
	s_nop 0
	buffer_load_dwordx4 v220, s[20:23], s13 offen lds
	s_nop 0
	s_mov_b32 m0, s79
	s_nop 0
	buffer_load_dwordx4 v221, s[20:23], s13 offen lds
	s_waitcnt vmcnt(8) lgkmcnt(0)
	s_barrier
	s_waitcnt lgkmcnt(7)
	v_mfma_f32_16x16x32_bf16 v[164:167], v[128:131], v[184:187], v[164:167]
	v_mfma_f32_16x16x32_bf16 v[160:163], v[152:155], v[184:187], v[160:163]
	s_waitcnt lgkmcnt(5)
	v_mfma_f32_16x16x32_bf16 v[136:139], v[128:131], v[192:195], v[136:139]
	v_mfma_f32_16x16x32_bf16 v[132:135], v[152:155], v[192:195], v[132:135]
	s_waitcnt lgkmcnt(3)
	v_mfma_f32_16x16x32_bf16 v[116:119], v[128:131], v[200:203], v[116:119]
	v_mfma_f32_16x16x32_bf16 v[112:115], v[152:155], v[200:203], v[112:115]
	s_waitcnt lgkmcnt(1)
	v_mfma_f32_16x16x32_bf16 v[76:79], v[128:131], v[224:227], v[76:79]
	v_mfma_f32_16x16x32_bf16 v[72:75], v[152:155], v[224:227], v[72:75]
	v_mfma_f32_16x16x32_bf16 v[164:167], v[140:143], v[188:191], v[164:167]
	v_mfma_f32_16x16x32_bf16 v[160:163], v[156:159], v[188:191], v[160:163]
	v_mfma_f32_16x16x32_bf16 v[136:139], v[140:143], v[196:199], v[136:139]
	v_mfma_f32_16x16x32_bf16 v[132:135], v[156:159], v[196:199], v[132:135]
	v_mfma_f32_16x16x32_bf16 v[116:119], v[140:143], v[204:207], v[116:119]
	v_mfma_f32_16x16x32_bf16 v[112:115], v[156:159], v[204:207], v[112:115]
	s_waitcnt lgkmcnt(0)
	v_mfma_f32_16x16x32_bf16 v[76:79], v[140:143], v[228:231], v[76:79]
	v_mfma_f32_16x16x32_bf16 v[72:75], v[156:159], v[228:231], v[72:75]
	v_mfma_f32_16x16x32_bf16 v[148:151], v[168:171], v[184:187], v[148:151]
	v_mfma_f32_16x16x32_bf16 v[144:147], v[176:179], v[184:187], v[144:147]
	v_mfma_f32_16x16x32_bf16 v[124:127], v[168:171], v[192:195], v[124:127]
	v_mfma_f32_16x16x32_bf16 v[120:123], v[176:179], v[192:195], v[120:123]
	v_mfma_f32_16x16x32_bf16 v[108:111], v[168:171], v[200:203], v[108:111]
	v_mfma_f32_16x16x32_bf16 v[104:107], v[176:179], v[200:203], v[104:107]
	v_mfma_f32_16x16x32_bf16 v[68:71], v[168:171], v[224:227], v[68:71]
	v_mfma_f32_16x16x32_bf16 v[64:67], v[176:179], v[224:227], v[64:67]
	v_mfma_f32_16x16x32_bf16 v[148:151], v[172:175], v[188:191], v[148:151]
	v_mfma_f32_16x16x32_bf16 v[144:147], v[180:183], v[188:191], v[144:147]
	v_mfma_f32_16x16x32_bf16 v[124:127], v[172:175], v[196:199], v[124:127]
	v_mfma_f32_16x16x32_bf16 v[120:123], v[180:183], v[196:199], v[120:123]
	v_mfma_f32_16x16x32_bf16 v[108:111], v[172:175], v[204:207], v[108:111]
	v_mfma_f32_16x16x32_bf16 v[104:107], v[180:183], v[204:207], v[104:107]
	v_mfma_f32_16x16x32_bf16 v[68:71], v[172:175], v[228:231], v[68:71]
	v_mfma_f32_16x16x32_bf16 v[64:67], v[180:183], v[228:231], v[64:67]
	s_barrier
	ds_read_b128 v[184:187], v223 offset:49152
	ds_read_b128 v[188:191], v223 offset:50176
	ds_read_b128 v[192:195], v223 offset:51200
	ds_read_b128 v[196:199], v223 offset:52224
	ds_read_b128 v[200:203], v223 offset:53248
	ds_read_b128 v[204:207], v223 offset:54272
	ds_read_b128 v[224:227], v223 offset:55296
	ds_read_b128 v[228:231], v223 offset:56320
	s_or_b32 s13, s12, 0x4000
	s_mov_b32 m0, s34
	s_nop 0
	buffer_load_dwordx4 v220, s[52:55], s13 offen lds
	s_add_i32 s12, s12, 0x164000
	s_mov_b32 m0, s82
	s_nop 0
	buffer_load_dwordx4 v221, s[52:55], s13 offen lds
	s_nop 0
	s_mov_b32 m0, s85
	s_nop 0
	buffer_load_dwordx4 v220, s[52:55], s12 offen lds
	s_nop 0
	s_mov_b32 m0, s86
	s_nop 0
	buffer_load_dwordx4 v221, s[52:55], s12 offen lds
	s_nop 0
	s_mov_b32 m0, s83
	s_nop 0
	buffer_load_dwordx4 v220, s[20:23], s11 offen lds
	s_nop 0
	s_mov_b32 m0, s84
	s_nop 0
	buffer_load_dwordx4 v221, s[20:23], s11 offen lds
	s_waitcnt vmcnt(8) lgkmcnt(0)
	s_barrier
	s_waitcnt lgkmcnt(7)
	v_mfma_f32_16x16x32_bf16 v[60:63], v[128:131], v[184:187], v[60:63]
	v_mfma_f32_16x16x32_bf16 v[56:59], v[152:155], v[184:187], v[56:59]
	s_waitcnt lgkmcnt(5)
	v_mfma_f32_16x16x32_bf16 v[44:47], v[128:131], v[192:195], v[44:47]
	v_mfma_f32_16x16x32_bf16 v[40:43], v[152:155], v[192:195], v[40:43]
	s_waitcnt lgkmcnt(3)
	v_mfma_f32_16x16x32_bf16 v[28:31], v[128:131], v[200:203], v[28:31]
	v_mfma_f32_16x16x32_bf16 v[24:27], v[152:155], v[200:203], v[24:27]
	s_waitcnt lgkmcnt(1)
	v_mfma_f32_16x16x32_bf16 v[12:15], v[128:131], v[224:227], v[12:15]
	v_mfma_f32_16x16x32_bf16 v[8:11], v[152:155], v[224:227], v[8:11]
	v_mfma_f32_16x16x32_bf16 v[60:63], v[140:143], v[188:191], v[60:63]
	v_mfma_f32_16x16x32_bf16 v[56:59], v[156:159], v[188:191], v[56:59]
	v_mfma_f32_16x16x32_bf16 v[44:47], v[140:143], v[196:199], v[44:47]
	v_mfma_f32_16x16x32_bf16 v[40:43], v[156:159], v[196:199], v[40:43]
	v_mfma_f32_16x16x32_bf16 v[28:31], v[140:143], v[204:207], v[28:31]
	v_mfma_f32_16x16x32_bf16 v[24:27], v[156:159], v[204:207], v[24:27]
	s_waitcnt lgkmcnt(0)
	v_mfma_f32_16x16x32_bf16 v[12:15], v[140:143], v[228:231], v[12:15]
	v_mfma_f32_16x16x32_bf16 v[8:11], v[156:159], v[228:231], v[8:11]
	v_mfma_f32_16x16x32_bf16 v[52:55], v[168:171], v[184:187], v[52:55]
	v_mfma_f32_16x16x32_bf16 v[48:51], v[176:179], v[184:187], v[48:51]
	v_mfma_f32_16x16x32_bf16 v[36:39], v[168:171], v[192:195], v[36:39]
	v_mfma_f32_16x16x32_bf16 v[32:35], v[176:179], v[192:195], v[32:35]
	v_mfma_f32_16x16x32_bf16 v[20:23], v[168:171], v[200:203], v[20:23]
	v_mfma_f32_16x16x32_bf16 v[16:19], v[176:179], v[200:203], v[16:19]
	v_mfma_f32_16x16x32_bf16 v[4:7], v[168:171], v[224:227], v[4:7]
	v_mfma_f32_16x16x32_bf16 v[0:3], v[176:179], v[224:227], v[0:3]
	v_mfma_f32_16x16x32_bf16 v[52:55], v[172:175], v[188:191], v[52:55]
	v_mfma_f32_16x16x32_bf16 v[48:51], v[180:183], v[188:191], v[48:51]
	v_mfma_f32_16x16x32_bf16 v[36:39], v[172:175], v[196:199], v[36:39]
	v_mfma_f32_16x16x32_bf16 v[32:35], v[180:183], v[196:199], v[32:35]
	v_mfma_f32_16x16x32_bf16 v[20:23], v[172:175], v[204:207], v[20:23]
	v_mfma_f32_16x16x32_bf16 v[16:19], v[180:183], v[204:207], v[16:19]
	v_mfma_f32_16x16x32_bf16 v[4:7], v[172:175], v[228:231], v[4:7]
	v_mfma_f32_16x16x32_bf16 v[0:3], v[180:183], v[228:231], v[0:3]
	s_barrier
	s_add_i32 s10, s10, 2
	s_add_i32 s8, s8, 0x8000
	s_add_i32 s9, s9, 0x8000
	s_cmpk_gt_u32 s10, 0x55
	s_cbranch_scc0 .LBB0_885
